# all three recurrent stream loops (GLA, HGRN2, mLSTM): gate-value rotation at chunk start and counted staging waits with a two-chunk load lead
# speedup vs baseline: 1.0028x; 1.0028x over previous
.LBB0_924:
	s_or_b64 exec, exec, s[8:9]
	s_sub_i32 s2, s93, 32
	s_lshr_b32 s3, s2, 2
	s_lshl_b32 s2, s93, 7
	s_lshl_b32 s8, s3, 13
	s_and_b32 s4, s2, 0x180
	s_lshl_b32 s3, s3, 9
	s_or_b32 s3, s3, s4
	s_lshl_b32 s2, s96, 4
	s_mul_i32 s10, s3, 0x6400
	s_add_u32 s18, s89, s10
	v_ashrrev_i32_e32 v151, 31, v150
	v_ashrrev_i32_e32 v43, 4, v148
	s_addc_u32 s19, s90, 0
	v_lshlrev_b64 v[40:41], 4, v[150:151]
	v_lshlrev_b32_e32 v69, 2, v43
	v_lshl_add_u64 v[24:25], s[18:19], 0, v[40:41]
	s_movk_i32 s3, 0x2000
	v_add_u32_e32 v0, s2, v69
	v_add_co_u32_e32 v4, vcc, s3, v24
	v_add_u32_e32 v70, s4, v0
	s_nop 0
	v_addc_co_u32_e32 v5, vcc, 0, v25, vcc
	s_movk_i32 s4, 0x4000
	s_add_u32 s20, s18, 0x6000
	v_ashrrev_i32_e32 v149, 31, v148
	v_lshlrev_b32_e32 v1, 15, v70
	v_and_b32_e32 v0, 60, v0
	s_mov_b32 s5, 0xffe00000
	v_add_co_u32_e32 v8, vcc, s4, v24
	s_addc_u32 s21, s19, 0
	v_lshlrev_b64 v[44:45], 2, v[148:149]
	s_mov_b32 s16, 0
	v_and_or_b32 v0, v1, s5, v0
	v_addc_co_u32_e32 v9, vcc, 0, v25, vcc
	v_lshl_add_u64 v[12:13], s[20:21], 0, v[44:45]
	v_ashrrev_i32_e32 v54, 3, v150
	v_ashrrev_i32_e32 v152, 4, v150
	s_mov_b32 s9, s16
	v_add_u32_e32 v42, 0x3000000, v0
	global_load_dwordx4 v[0:3], v[24:25], off
	s_nop 0
	global_load_dwordx4 v[4:7], v[4:5], off
	s_nop 0
	global_load_dwordx4 v[8:11], v[8:9], off
	s_nop 0
	global_load_dword v149, v[12:13], off
	global_load_dword v151, v[12:13], off offset:256
	global_load_dword v156, v[12:13], off offset:512
	v_ashrrev_i32_e32 v55, 31, v54
	v_and_b32_e32 v12, 63, v148
	v_ashrrev_i32_e32 v153, 31, v152
	v_lshlrev_b64 v[46:47], 2, v[54:55]
	v_lshlrev_b32_e32 v55, 2, v12
	v_lshl_add_u64 v[12:13], s[8:9], 0, v[152:153]
	s_lshl_b32 s5, s93, 23
	v_lshlrev_b64 v[48:49], 9, v[12:13]
	s_and_b32 s12, s5, 0x1000000
	v_lshl_add_u64 v[12:13], s[60:61], 0, v[48:49]
	s_or_b32 s22, s12, 0x16000000
	s_mov_b32 s23, s16
	s_lshl_b32 s5, s93, 8
	v_lshlrev_b32_e32 v14, 3, v148
	v_lshl_add_u64 v[12:13], v[12:13], 0, s[22:23]
	s_and_b32 s14, s5, 0x100
	s_mov_b32 s15, s16
	v_and_b32_e32 v180, 0x78, v14
	v_mov_b32_e32 v73, 0
	v_lshl_add_u64 v[12:13], v[12:13], 0, s[14:15]
	v_lshlrev_b32_e32 v72, 1, v180
	v_lshl_add_u64 v[30:31], v[12:13], 0, v[72:73]
	v_add_u32_e32 v12, 0x200, v150
	v_ashrrev_i32_e32 v56, 4, v12
	v_ashrrev_i32_e32 v57, 31, v56
	v_and_b32_e32 v68, 15, v148
	v_add_u32_e32 v16, 0x1800, v70
	v_lshl_add_u64 v[12:13], s[8:9], 0, v[56:57]
	v_lshlrev_b64 v[52:53], 9, v[12:13]
	v_or_b32_e32 v50, s8, v68
	v_mov_b32_e32 v51, v73
	v_ashrrev_i32_e32 v16, 8, v16
	v_lshl_add_u64 v[12:13], s[60:61], 0, v[52:53]
	v_lshlrev_b64 v[58:59], 9, v[50:51]
	v_ashrrev_i32_e32 v17, 31, v16
	v_lshl_add_u64 v[12:13], v[12:13], 0, s[22:23]
	v_lshl_add_u64 v[14:15], s[60:61], 0, v[58:59]
	v_and_b32_e32 v18, 0xfc, v70
	v_lshlrev_b64 v[60:61], 24, v[16:17]
	v_lshl_add_u64 v[12:13], v[12:13], 0, s[14:15]
	v_lshl_add_u64 v[14:15], v[14:15], 0, v[60:61]
	v_lshlrev_b32_e32 v36, 1, v18
	v_mov_b32_e32 v37, v73
	v_lshl_add_u64 v[12:13], v[12:13], 0, v[72:73]
	v_lshl_add_u64 v[62:63], v[14:15], 0, v[36:37]
	global_load_dwordx4 v[20:23], v[12:13], off
	global_load_dwordx2 v[102:103], v[62:63], off
	v_add_co_u32_e32 v12, vcc, s3, v62
	s_movk_i32 s3, 0x6000
	s_nop 0
	v_addc_co_u32_e32 v13, vcc, 0, v63, vcc
	v_add_co_u32_e32 v14, vcc, s4, v62
	s_add_u32 s4, s18, 0xc400
	s_nop 0
	v_addc_co_u32_e32 v15, vcc, 0, v63, vcc
	v_add_co_u32_e32 v16, vcc, s3, v62
	s_addc_u32 s5, s19, 0
	s_nop 0
	v_addc_co_u32_e32 v17, vcc, 0, v63, vcc
	global_load_dwordx2 v[104:105], v[12:13], off
	global_load_dwordx2 v[106:107], v[14:15], off
	global_load_dwordx2 v[108:109], v[16:17], off
	v_add_co_u32_e32 v12, vcc, s3, v24
	s_mov_b32 s3, 0x8000
	s_nop 0
	v_addc_co_u32_e32 v13, vcc, 0, v25, vcc
	v_add_co_u32_e32 v16, vcc, s3, v24
	s_mov_b32 s3, 0xa000
	s_nop 0
	v_addc_co_u32_e32 v17, vcc, 0, v25, vcc
	v_add_co_u32_e32 v24, vcc, s3, v24
	v_lshl_add_u64 v[28:29], s[20:21], 0, v[46:47]
	s_nop 0
	v_addc_co_u32_e32 v25, vcc, 0, v25, vcc
	v_lshl_add_u64 v[32:33], s[4:5], 0, v[44:45]
	global_load_dwordx4 v[12:15], v[12:13], off offset:1024
	s_nop 0
	global_load_dwordx4 v[16:19], v[16:17], off offset:1024
	s_nop 0
	global_load_dwordx4 v[24:27], v[24:25], off offset:1024
	s_nop 0
	global_load_dword v157, v[32:33], off
	global_load_dword v158, v[32:33], off offset:256
	global_load_dword v159, v[32:33], off offset:512
	v_lshl_add_u64 v[32:33], s[4:5], 0, v[46:47]
	global_load_dword v160, v[28:29], off offset:256
	global_load_dword v203, v55, s[20:21] offset:768
	s_nop 0
	global_load_dwordx4 v[28:31], v[30:31], off
	s_nop 0
	global_load_dword v100, v55, s[4:5] offset:768
	s_or_b32 s4, s8, 64
	s_mov_b32 s5, s16
	v_lshl_add_u64 v[34:35], s[4:5], 0, v[152:153]
	v_lshl_add_u64 v[38:39], s[4:5], 0, v[56:57]
	v_lshlrev_b64 v[34:35], 9, v[34:35]
	v_lshlrev_b64 v[38:39], 9, v[38:39]
	v_lshl_add_u64 v[34:35], s[60:61], 0, v[34:35]
	v_lshl_add_u64 v[38:39], s[60:61], 0, v[38:39]
	v_lshl_add_u64 v[34:35], v[34:35], 0, s[22:23]
	v_lshl_add_u64 v[38:39], v[38:39], 0, s[22:23]
	v_lshl_add_u64 v[34:35], v[34:35], 0, s[14:15]
	v_lshl_add_u64 v[38:39], v[38:39], 0, s[14:15]
	v_lshl_add_u64 v[34:35], v[34:35], 0, v[72:73]
	v_lshl_add_u64 v[38:39], v[38:39], 0, v[72:73]
	v_or_b32_e32 v72, s4, v68
	v_lshlrev_b64 v[64:65], 9, v[72:73]
	v_lshl_add_u64 v[64:65], s[60:61], 0, v[64:65]
	v_lshl_add_u64 v[64:65], v[64:65], 0, v[60:61]
	v_lshl_add_u64 v[64:65], v[64:65], 0, v[36:37]
	global_load_dword v165, v[32:33], off offset:256
	s_nop 0
	global_load_dwordx4 v[32:35], v[34:35], off
	s_nop 0
	global_load_dwordx4 v[36:39], v[38:39], off
	s_nop 0
	global_load_dwordx2 v[98:99], v[64:65], off
	v_add_co_u32_e32 v64, vcc, s3, v62
	s_mov_b32 s3, 0xc000
	s_nop 0
	v_addc_co_u32_e32 v65, vcc, 0, v63, vcc
	v_add_co_u32_e32 v66, vcc, s3, v62
	s_mov_b32 s3, 0xe000
	s_nop 0
	v_addc_co_u32_e32 v67, vcc, 0, v63, vcc
	v_add_co_u32_e32 v62, vcc, s3, v62
	s_cmp_eq_u32 s96, 0
	s_nop 0
	v_addc_co_u32_e32 v63, vcc, 0, v63, vcc
	global_load_dwordx2 v[96:97], v[64:65], off
	global_load_dwordx2 v[80:81], v[66:67], off
	global_load_dwordx2 v[74:75], v[62:63], off
	s_cselect_b64 s[20:21], -1, 0
	v_lshlrev_b32_e32 v51, 2, v148
	s_add_i32 s3, 0, 0x11c00
	s_add_i32 s13, 0, 0x11d00
	s_add_i32 s15, 0, 0x11e00
	s_add_i32 s17, 0, 0x11f00
	v_add_u32_e32 v161, s3, v51
	v_add_u32_e32 v162, s13, v51
	v_add_u32_e32 v163, s15, v51
	v_add_u32_e32 v164, s17, v51
	v_lshlrev_b32_e32 v51, 3, v150
	v_and_b32_e32 v51, 56, v51
	s_movk_i32 s18, 0x90
	v_mul_lo_u32 v54, v54, s18
	v_lshlrev_b32_e32 v57, 1, v51
	v_readlane_b32 s45, v250, 16
	v_add3_u32 v166, 0, v54, v57
	v_and_b32_e32 v54, 7, v148
	v_lshl_add_u32 v167, v51, 2, s45
	v_and_b32_e32 v51, 0x3ffffff8, v150
	s_add_i32 s19, 0, 0x12100
	v_lshlrev_b32_e32 v51, 2, v51
	v_lshlrev_b32_e32 v54, 2, v54
	s_lshl_b32 s4, s96, 1
	v_add3_u32 v168, s19, v51, v54
	s_movk_i32 s33, 0x110
	v_lshlrev_b32_e32 v54, 4, v150
	s_ashr_i32 s26, s96, 1
	s_and_b32 s44, s4, 2
	v_mul_lo_u32 v51, v152, s33
	v_and_b32_e32 v54, 0xf0, v54
	s_cmp_le_i32 s44, s26
	v_add3_u32 v169, 0, v51, v54
	v_mul_lo_u32 v51, v56, s33
	s_cselect_b64 s[22:23], -1, 0
	s_cmp_gt_i32 s44, s26
	v_add3_u32 v170, 0, v51, v54
	s_cselect_b64 s[4:5], -1, 0
	s_cmp_lt_i32 s44, s26
	v_mul_u32_u24_e32 v51, 0x90, v68
	v_lshlrev_b32_e32 v171, 3, v43
	v_and_b32_e32 v43, -16, v148
	s_cselect_b64 s[24:25], -1, 0
	s_cmp_ge_i32 s44, s26
	v_add3_u32 v172, 0, v51, v43
	v_or_b32_e32 v51, s2, v68
	s_cselect_b64 s[8:9], -1, 0
	v_mul_lo_u32 v51, v51, s18
	s_lshl_b32 s27, s44, 4
	v_add_u32_e32 v173, 0, v51
	v_or_b32_e32 v51, s27, v68
	v_mul_u32_u24_e32 v51, 0x90, v51
	v_add3_u32 v175, 0, v51, v43
	v_lshlrev_b32_e32 v51, 2, v68
	v_add_u32_e32 v176, s17, v51
	s_lshl_b32 s17, s26, 6
	s_add_i32 s13, s13, s17
	v_add_u32_e32 v177, s13, v51
	s_lshl_b32 s13, s44, 6
	s_add_i32 s3, s3, s13
	v_add_u32_e32 v174, v173, v43
	v_add_u32_e32 v178, s3, v43
	v_add_u32_e32 v43, s27, v69
	v_lshl_or_b32 v56, s26, 4, v68
	v_add_u32_e32 v57, 16, v43
	v_cmp_gt_i32_e32 vcc, v43, v56
	s_mul_i32 s2, s26, 0x900
	s_or_b64 s[26:27], s[4:5], vcc
	v_cmp_gt_i32_e32 vcc, v57, v56
	s_or_b64 s[28:29], s[8:9], vcc
	v_cmp_ge_i32_e32 vcc, v43, v56
	s_or_b64 s[30:31], s[4:5], vcc
	v_cmp_ge_i32_e32 vcc, v57, v56
	v_or_b32_e32 v57, 2, v43
	s_lshl_b32 s3, s44, 2
	s_or_b64 s[34:35], s[8:9], vcc
	v_cmp_gt_i32_e32 vcc, v57, v56
	v_add_u32_e32 v57, 18, v43
	s_add_i32 s3, s3, 0
	s_or_b64 s[36:37], s[4:5], vcc
	v_cmp_gt_i32_e32 vcc, v57, v56
	v_or_b32_e32 v57, 3, v43
	s_add_i32 s3, s3, 0x12900
	s_or_b64 s[38:39], s[8:9], vcc
	v_cmp_gt_i32_e32 vcc, v57, v56
	v_add_u32_e32 v43, 19, v43
	v_lshl_add_u32 v179, v56, 4, s3
	s_lshl_b32 s3, s44, 5
	s_or_b64 s[40:41], s[4:5], vcc
	v_cmp_gt_i32_e32 vcc, v43, v56
	v_mul_lo_u32 v43, v56, s18
	s_add_i32 s3, s3, 0
	v_add_u32_e32 v56, s3, v43
	v_ashrrev_i32_e32 v43, 1, v148
	v_bfe_u32 v202, v148, 2, 2
	v_and_or_b32 v43, v43, -8, v202
	v_mul_lo_u32 v63, v43, s33
	v_mul_lo_u32 v64, v43, s18
	v_ashrrev_i32_e32 v43, 31, v42
	v_lshl_add_u64 v[76:77], v[42:43], 1, s[64:65]
	v_or_b32_e32 v42, 16, v68
	s_lshl_b32 s3, s96, 5
	v_and_b32_e32 v201, 12, v200
	v_lshlrev_b32_e32 v43, 5, v42
	v_lshlrev_b32_e32 v187, 4, v42
	v_lshl_add_u32 v188, v42, 2, s15
	v_or_b32_e32 v42, 32, v68
	s_waitcnt vmcnt(0) lgkmcnt(0)
	s_barrier
	s_add_i32 s3, s3, 0
	v_lshlrev_b32_e32 v57, 1, v201
	v_add_u32_e32 v186, s15, v51
	v_lshlrev_b32_e32 v51, 5, v42
	v_lshlrev_b32_e32 v189, 4, v42
	v_lshl_add_u32 v190, v42, 2, s15
	v_or_b32_e32 v42, 48, v68
	s_mov_b32 s13, s16
	s_mov_b32 s11, s16
	v_add_u32_e32 v62, s3, v57
	v_add_u32_e32 v57, 0, v57
	v_lshlrev_b32_e32 v65, 5, v68
	v_lshlrev_b32_e32 v66, 5, v42
	v_lshlrev_b32_e32 v191, 4, v42
	v_lshl_add_u32 v192, v42, 2, s15
	v_lshl_add_u64 v[78:79], v[60:61], 0, v[58:59]
	v_lshlrev_b32_e32 v42, 1, v70
	s_movk_i32 s3, 0x1f8
	v_lshl_add_u64 v[82:83], s[12:13], 0, v[52:53]
	v_lshl_add_u64 v[84:85], s[12:13], 0, v[48:49]
	v_or_b32_e32 v72, s10, v55
	v_mov_b32_e32 v181, v73
	s_or_b64 s[42:43], s[8:9], vcc
	v_cmp_gt_u32_e64 s[8:9], 16, v148
	v_add_u32_e32 v182, 0xf800, v172
	v_add_u32_e32 v183, 0xf840, v172
	v_lshl_add_u32 v184, v150, 2, s45
	v_lshlrev_b32_e32 v185, 4, v68
	v_and_or_b32 v78, v42, s3, v78
	v_or3_b32 v82, v82, s14, v54
	v_or3_b32 v84, v84, s14, v54
	v_lshl_add_u64 v[86:87], v[40:41], 0, s[10:11]
	v_lshl_add_u64 v[88:89], v[44:45], 0, s[10:11]
	v_lshl_add_u64 v[90:91], v[46:47], 0, s[10:11]
	v_or_b32_e32 v92, 0x70, v50
	s_mov_b64 s[44:45], 0x10000
	s_mov_b64 s[46:47], 0xc800
	v_add_u32_e32 v193, v56, v171
	v_add_u32_e32 v194, v62, v63
	v_add_u32_e32 v195, v57, v64
	v_add_u32_e32 v196, s19, v65
	v_add_u32_e32 v197, s19, v43
	v_add_u32_e32 v198, s19, v51
	v_add_u32_e32 v199, s19, v66
	v_mov_b64_e32 v[94:95], v[72:73]
	v_mov_b32_e32 v101, 0
	s_mov_b32 s3, 0
	v_mov_b32_e32 v118, v73
	v_mov_b32_e32 v119, v73
	v_mov_b32_e32 v126, v73
	v_mov_b32_e32 v127, v73
	v_mov_b32_e32 v120, v73
	v_mov_b32_e32 v121, v73
	v_mov_b32_e32 v128, v73
	v_mov_b32_e32 v129, v73
	v_mov_b32_e32 v122, v73
	v_mov_b32_e32 v123, v73
	v_mov_b32_e32 v130, v73
	v_mov_b32_e32 v131, v73
	v_mov_b32_e32 v124, v73
	v_mov_b32_e32 v125, v73
	v_mov_b32_e32 v132, v73
	v_mov_b32_e32 v133, v73
	s_branch .LBB0_926
.LBB0_925:
	s_or_b64 exec, exec, s[10:11]
	ds_read_b128 v[56:59], v196
	ds_read_b128 v[60:63], v196 offset:16
	ds_read_b128 v[64:67], v205
	v_mov_b32_e32 v68, s5
	v_add_f32_e32 v101, s4, v68
	v_subrev_u32_e32 v72, 48, v92
	s_waitcnt lgkmcnt(2)
	v_add_f32_e32 v68, v56, v57
	v_add_f32_e32 v70, v58, v59
	s_waitcnt lgkmcnt(1)
	v_add_f32_e32 v60, v60, v61
	v_add_f32_e32 v62, v62, v63
	s_waitcnt lgkmcnt(0)
	v_mov_b32_e32 v69, v64
	v_mov_b32_e32 v71, v65
	v_mov_b32_e32 v61, v66
	v_mov_b32_e32 v63, v67
	ds_read_b128 v[56:59], v197
	ds_read_b32 v66, v186
	v_pk_add_f32 v[64:65], v[68:69], v[70:71]
	v_pk_add_f32 v[60:61], v[60:61], v[62:63]
	v_and_b32_e32 v62, 0xffff0000, v116
	v_pk_add_f32 v[60:61], v[64:65], v[60:61]
	v_mul_f32_e32 v62, 0xbfb8aa3b, v62
	v_add_f32_e32 v60, v60, v61
	v_lshlrev_b32_e32 v61, 16, v116
	v_mul_f32_e32 v61, 0xbfb8aa3b, v61
	v_exp_f32_e32 v61, v61
	s_waitcnt lgkmcnt(0)
	v_mul_f32_e32 v66, 0xbfb8aa3b, v66
	v_exp_f32_e32 v63, v62
	v_exp_f32_e32 v66, v66
	v_add_f32_e32 v61, 1.0, v61
	v_lshlrev_b32_e32 v64, 16, v117
	v_rcp_f32_e32 v62, v61
	v_add_f32_e32 v61, 1.0, v63
	v_max_f32_e64 v60, |v60|, v66
	v_and_b32_e32 v65, 0xffff0000, v117
	v_rcp_f32_e32 v63, v61
	v_mul_f32_e32 v61, 0xbfb8aa3b, v64
	v_rcp_f32_e32 v60, v60
	v_exp_f32_e32 v61, v61
	v_mul_f32_e32 v64, 0xbfb8aa3b, v65
	v_exp_f32_e32 v65, v64
	ds_read_b32 v67, v188
	ds_read_b32 v68, v190
	ds_read_b32 v69, v192
	v_pk_mul_f32 v[52:53], v[52:53], v[60:61] op_sel_hi:[1,0]
	v_add_f32_e32 v61, 1.0, v61
	v_rcp_f32_e32 v64, v61
	v_add_f32_e32 v61, 1.0, v65
	v_rcp_f32_e32 v65, v61
	v_pk_mul_f32 v[52:53], v[62:63], v[52:53]
	v_add_f32_e32 v56, v56, v57
	v_cvt_pk_bf16_f32 v62, v52, v53
	v_pk_mul_f32 v[52:53], v[54:55], v[60:61] op_sel_hi:[1,0]
	v_add_f32_e32 v58, v58, v59
	v_pk_mul_f32 v[52:53], v[64:65], v[52:53]
	v_mov_b32_e32 v93, v73
	v_cvt_pk_bf16_f32 v63, v52, v53
	v_lshlrev_b64 v[52:53], 7, v[72:73]
	v_lshl_add_u64 v[60:61], v[76:77], 0, v[52:53]
	ds_read_b128 v[52:55], v197 offset:16
	global_store_dwordx2 v[60:61], v[62:63], off
	ds_read_b128 v[60:63], v206
	v_subrev_u32_e32 v72, 32, v92
	s_add_i32 s3, s3, 2
	s_waitcnt lgkmcnt(1)
	v_add_f32_e32 v52, v52, v53
	v_add_f32_e32 v54, v54, v55
	s_waitcnt lgkmcnt(0)
	v_mov_b32_e32 v57, v60
	v_mov_b32_e32 v59, v61
	v_mov_b32_e32 v53, v62
	v_mov_b32_e32 v55, v63
	v_pk_add_f32 v[56:57], v[56:57], v[58:59]
	v_pk_add_f32 v[52:53], v[52:53], v[54:55]
	v_and_b32_e32 v54, 0xffff0000, v114
	v_pk_add_f32 v[52:53], v[56:57], v[52:53]
	v_mul_f32_e32 v54, 0xbfb8aa3b, v54
	v_add_f32_e32 v52, v52, v53
	v_lshlrev_b32_e32 v53, 16, v114
	v_mul_f32_e32 v53, 0xbfb8aa3b, v53
	v_exp_f32_e32 v53, v53
	v_mul_f32_e32 v58, 0xbfb8aa3b, v67
	v_exp_f32_e32 v55, v54
	v_exp_f32_e32 v58, v58
	v_add_f32_e32 v53, 1.0, v53
	v_lshlrev_b32_e32 v56, 16, v115
	v_rcp_f32_e32 v54, v53
	v_add_f32_e32 v53, 1.0, v55
	v_max_f32_e64 v52, |v52|, v58
	v_and_b32_e32 v57, 0xffff0000, v115
	v_rcp_f32_e32 v55, v53
	v_mul_f32_e32 v53, 0xbfb8aa3b, v56
	v_rcp_f32_e32 v52, v52
	v_exp_f32_e32 v53, v53
	v_mul_f32_e32 v56, 0xbfb8aa3b, v57
	v_exp_f32_e32 v57, v56
	v_lshl_add_u64 v[78:79], v[78:79], 0, s[44:45]
	v_pk_mul_f32 v[48:49], v[48:49], v[52:53] op_sel_hi:[1,0]
	v_add_f32_e32 v53, 1.0, v53
	v_rcp_f32_e32 v56, v53
	v_add_f32_e32 v53, 1.0, v57
	v_rcp_f32_e32 v57, v53
	v_pk_mul_f32 v[48:49], v[54:55], v[48:49]
	v_lshl_add_u64 v[82:83], v[82:83], 0, s[44:45]
	v_cvt_pk_bf16_f32 v58, v48, v49
	v_pk_mul_f32 v[48:49], v[50:51], v[52:53] op_sel_hi:[1,0]
	v_lshlrev_b64 v[52:53], 7, v[72:73]
	v_pk_mul_f32 v[48:49], v[56:57], v[48:49]
	v_lshl_add_u64 v[56:57], v[76:77], 0, v[52:53]
	v_cvt_pk_bf16_f32 v59, v48, v49
	ds_read_b128 v[48:51], v198
	ds_read_b128 v[52:55], v198 offset:16
	global_store_dwordx2 v[56:57], v[58:59], off
	ds_read_b128 v[56:59], v207
	v_add_u32_e32 v72, -16, v92
	s_waitcnt lgkmcnt(2)
	v_add_f32_e32 v60, v48, v49
	v_add_f32_e32 v62, v50, v51
	s_waitcnt lgkmcnt(1)
	v_add_f32_e32 v52, v52, v53
	v_add_f32_e32 v54, v54, v55
	s_waitcnt lgkmcnt(0)
	v_mov_b32_e32 v61, v56
	v_mov_b32_e32 v63, v57
	v_mov_b32_e32 v53, v58
	v_mov_b32_e32 v55, v59
	v_pk_add_f32 v[56:57], v[60:61], v[62:63]
	v_pk_add_f32 v[52:53], v[52:53], v[54:55]
	v_and_b32_e32 v54, 0xffff0000, v112
	v_pk_add_f32 v[52:53], v[56:57], v[52:53]
	v_mul_f32_e32 v54, 0xbfb8aa3b, v54
	v_add_f32_e32 v52, v52, v53
	v_lshlrev_b32_e32 v53, 16, v112
	v_mul_f32_e32 v53, 0xbfb8aa3b, v53
	v_exp_f32_e32 v53, v53
	v_mul_f32_e32 v58, 0xbfb8aa3b, v68
	v_exp_f32_e32 v55, v54
	v_exp_f32_e32 v58, v58
	v_add_f32_e32 v53, 1.0, v53
	v_lshlrev_b32_e32 v56, 16, v113
	v_rcp_f32_e32 v54, v53
	v_add_f32_e32 v53, 1.0, v55
	v_max_f32_e64 v52, |v52|, v58
	v_and_b32_e32 v57, 0xffff0000, v113
	v_rcp_f32_e32 v55, v53
	v_mul_f32_e32 v53, 0xbfb8aa3b, v56
	v_rcp_f32_e32 v52, v52
	v_exp_f32_e32 v53, v53
	v_mul_f32_e32 v56, 0xbfb8aa3b, v57
	v_exp_f32_e32 v57, v56
	ds_read_b128 v[48:51], v199
	v_pk_mul_f32 v[44:45], v[44:45], v[52:53] op_sel_hi:[1,0]
	v_add_f32_e32 v53, 1.0, v53
	v_rcp_f32_e32 v56, v53
	v_add_f32_e32 v53, 1.0, v57
	v_rcp_f32_e32 v57, v53
	v_pk_mul_f32 v[44:45], v[54:55], v[44:45]
	v_lshl_add_u64 v[84:85], v[84:85], 0, s[44:45]
	v_cvt_pk_bf16_f32 v54, v44, v45
	v_pk_mul_f32 v[44:45], v[46:47], v[52:53] op_sel_hi:[1,0]
	v_lshl_add_u64 v[86:87], v[86:87], 0, s[46:47]
	v_pk_mul_f32 v[44:45], v[56:57], v[44:45]
	v_lshl_add_u64 v[88:89], v[88:89], 0, s[46:47]
	v_cvt_pk_bf16_f32 v55, v44, v45
	v_lshlrev_b64 v[44:45], 7, v[72:73]
	v_lshl_add_u64 v[52:53], v[76:77], 0, v[44:45]
	ds_read_b128 v[44:47], v199 offset:16
	global_store_dwordx2 v[52:53], v[54:55], off
	ds_read_b128 v[52:55], v208
	s_waitcnt lgkmcnt(2)
	v_add_f32_e32 v48, v48, v49
	v_add_f32_e32 v50, v50, v51
	s_waitcnt lgkmcnt(1)
	v_add_f32_e32 v44, v44, v45
	v_add_f32_e32 v46, v46, v47
	s_waitcnt lgkmcnt(0)
	v_mov_b32_e32 v49, v52
	v_mov_b32_e32 v51, v53
	v_mov_b32_e32 v45, v54
	v_mov_b32_e32 v47, v55
	v_pk_add_f32 v[48:49], v[48:49], v[50:51]
	v_pk_add_f32 v[44:45], v[44:45], v[46:47]
	v_and_b32_e32 v46, 0xffff0000, v110
	v_pk_add_f32 v[44:45], v[48:49], v[44:45]
	v_mul_f32_e32 v46, 0xbfb8aa3b, v46
	v_add_f32_e32 v44, v44, v45
	v_lshlrev_b32_e32 v45, 16, v110
	v_mul_f32_e32 v45, 0xbfb8aa3b, v45
	v_exp_f32_e32 v45, v45
	v_mul_f32_e32 v50, 0xbfb8aa3b, v69
	v_exp_f32_e32 v47, v46
	v_exp_f32_e32 v50, v50
	v_add_f32_e32 v45, 1.0, v45
	v_lshlrev_b32_e32 v48, 16, v111
	v_rcp_f32_e32 v46, v45
	v_add_f32_e32 v45, 1.0, v47
	v_max_f32_e64 v44, |v44|, v50
	v_and_b32_e32 v49, 0xffff0000, v111
	v_rcp_f32_e32 v47, v45
	v_mul_f32_e32 v45, 0xbfb8aa3b, v48
	v_rcp_f32_e32 v44, v44
	v_exp_f32_e32 v45, v45
	v_mul_f32_e32 v48, 0xbfb8aa3b, v49
	v_exp_f32_e32 v49, v48
	v_lshl_add_u64 v[90:91], v[90:91], 0, s[46:47]
	v_pk_mul_f32 v[40:41], v[40:41], v[44:45] op_sel_hi:[1,0]
	v_add_f32_e32 v45, 1.0, v45
	v_rcp_f32_e32 v48, v45
	v_add_f32_e32 v45, 1.0, v49
	v_rcp_f32_e32 v49, v45
	v_pk_mul_f32 v[42:43], v[42:43], v[44:45] op_sel_hi:[1,0]
	v_pk_mul_f32 v[40:41], v[46:47], v[40:41]
	v_lshl_add_u64 v[94:95], v[94:95], 0, s[46:47]
	v_pk_mul_f32 v[42:43], v[48:49], v[42:43]
	v_cvt_pk_bf16_f32 v40, v40, v41
	v_cvt_pk_bf16_f32 v41, v42, v43
	v_lshlrev_b64 v[42:43], 7, v[92:93]
	v_lshl_add_u64 v[42:43], v[76:77], 0, v[42:43]
	global_store_dwordx2 v[42:43], v[40:41], off
	s_waitcnt lgkmcnt(0)
	s_barrier
	v_add_u32_e32 v92, 0x80, v92
	s_andn2_b64 vcc, exec, s[72:73]
	s_cbranch_vccz .LBB0_954
.LBB0_926:
	s_cmpk_lt_u32 s3, 0x7e
	s_cbranch_scc1 .Lsf_e
	s_waitcnt vmcnt(0)
.Lsf_e:
	s_waitcnt vmcnt(22)
	v_mov_b64_e32 v[116:117], v[102:103]
	v_mov_b64_e32 v[114:115], v[104:105]
	v_mov_b64_e32 v[112:113], v[106:107]
	v_mov_b64_e32 v[110:111], v[108:109]
	v_mov_b32_e32 v154, v203
	v_max_f32_e32 v41, v151, v151
	v_max_f32_e32 v40, v101, v101
	v_max_f32_e32 v41, v40, v41
	v_cndmask_b32_e64 v42, 0, 1, s[20:21]
	v_readlane_b32 s4, v41, 63
	v_readlane_b32 s33, v151, 63
	v_cmp_ne_u32_e64 s[14:15], 1, v42
	s_andn2_b64 vcc, exec, s[20:21]
	v_readlane_b32 s5, v156, 63
	s_cbranch_vccnz .LBB0_928
	v_sub_f32_e32 v43, v101, v41
	v_mul_f32_e32 v43, 0x3fb8aa3b, v43
	v_exp_f32_e32 v43, v43
	v_add_f32_e32 v42, v156, v41
	ds_write_b32 v161, v149
	ds_write_b32 v162, v41
	ds_write_b32 v163, v42
	ds_write_b32 v164, v43
.LBB0_928:
	ds_write_b128 v166, v[0:3]
	ds_write_b128 v166, v[4:7] offset:9216
	ds_write_b128 v166, v[8:11] offset:18432
	ds_read_b128 v[42:45], v167
	ds_read_b128 v[46:49], v167 offset:16
	v_max_f32_e32 v41, v160, v160
	v_lshlrev_b32_e32 v54, 16, v0
	v_and_b32_e32 v55, 0xffff0000, v1
	s_waitcnt lgkmcnt(1)
	v_mov_b32_e32 v52, v43
	v_mov_b32_e32 v43, v45
	v_max_f32_e32 v40, v40, v41
	v_and_b32_e32 v50, 0xffff0000, v0
	v_lshlrev_b32_e32 v51, 16, v1
	v_mov_b32_e32 v53, v44
	v_pk_mul_f32 v[42:43], v[42:43], v[54:55]
	v_sub_f32_e32 v40, v101, v40
	v_pk_fma_f32 v[42:43], v[52:53], v[50:51], v[42:43]
	s_waitcnt lgkmcnt(0)
	v_mov_b32_e32 v51, v48
	v_and_b32_e32 v53, 0xffff0000, v3
	v_and_b32_e32 v52, 0xffff0000, v2
	v_mov_b32_e32 v48, v47
	v_mul_f32_e32 v40, 0x3fb8aa3b, v40
	v_lshlrev_b32_e32 v45, 16, v3
	v_lshlrev_b32_e32 v44, 16, v2
	v_mov_b32_e32 v50, v46
	v_pk_mul_f32 v[46:47], v[48:49], v[52:53]
	v_exp_f32_e32 v40, v40
	v_pk_fma_f32 v[44:45], v[50:51], v[44:45], v[46:47]
	v_add_f32_e32 v41, v42, v43
	s_cmpk_lt_u32 s3, 0x7e
	v_add_f32_e32 v41, v44, v41
	s_cselect_b64 s[74:75], -1, 0
	s_cmpk_gt_u32 s3, 0x7d
	v_add_f32_e32 v41, v45, v41
	s_cselect_b64 s[72:73], -1, 0
	v_mul_f32_e32 v40, v40, v41
	s_and_b64 vcc, exec, s[72:73]
	v_lshl_add_u64 v[146:147], s[48:49], 0, v[86:87]
	v_lshl_add_u64 v[144:145], s[48:49], 0, v[88:89]
	v_lshl_add_u64 v[142:143], s[48:49], 0, v[90:91]
	v_lshl_add_u64 v[140:141], s[48:49], 0, v[94:95]
	v_lshl_add_u64 v[138:139], s[48:49], 0, v[84:85]
	v_lshl_add_u64 v[136:137], s[48:49], 0, v[82:83]
	v_lshl_add_u64 v[134:135], s[48:49], 0, v[78:79]
	ds_write_b32 v168, v40
	ds_write_b128 v169, v[28:31] offset:27648
	ds_write_b128 v170, v[20:23] offset:27648
	s_cbranch_vccnz .LBB0_930
	v_add_co_u32_e32 v0, vcc, 0x51b8c000, v146
	s_nop 1
	v_addc_co_u32_e32 v1, vcc, 0, v147, vcc
	v_add_co_u32_e32 v4, vcc, 0x51b8e000, v146
	s_nop 1
	v_addc_co_u32_e32 v5, vcc, 0, v147, vcc
	v_add_co_u32_e32 v8, vcc, 0x51b90000, v146
	global_load_dwordx4 v[0:3], v[0:1], off offset:2048
	s_nop 0
	global_load_dwordx4 v[4:7], v[4:5], off offset:2048
	v_addc_co_u32_e32 v9, vcc, 0, v147, vcc
	v_add_co_u32_e32 v20, vcc, 0x51b92000, v144
	s_nop 1
	v_addc_co_u32_e32 v21, vcc, 0, v145, vcc
	global_load_dwordx4 v[8:11], v[8:9], off offset:2048
	s_nop 0
	global_load_dword v149, v[20:21], off offset:2048
	global_load_dword v151, v[20:21], off offset:2304
	global_load_dword v156, v[20:21], off offset:2560
	v_add_co_u32_e32 v20, vcc, 0x51b92000, v142
	s_nop 1
	v_addc_co_u32_e32 v21, vcc, 0, v143, vcc
	v_add_co_u32_e32 v22, vcc, 0x51b92000, v140
	s_nop 1
	v_addc_co_u32_e32 v23, vcc, 0, v141, vcc
	v_add_co_u32_e32 v28, vcc, 0x40810000, v138
	s_nop 1
	v_addc_co_u32_e32 v29, vcc, 0, v139, vcc
	global_load_dword v160, v[20:21], off offset:2304
	global_load_dword v203, v[22:23], off offset:2816
	s_nop 0
	global_load_dwordx4 v[28:31], v[28:29], off
	v_add_co_u32_e32 v20, vcc, 0x40810000, v136
	s_nop 1
	v_addc_co_u32_e32 v21, vcc, 0, v137, vcc
	v_add_co_u32_e32 v40, vcc, 0x2a810000, v134
	s_nop 1
	v_addc_co_u32_e32 v41, vcc, 0, v135, vcc
	global_load_dwordx4 v[20:23], v[20:21], off
	s_nop 0
	global_load_dwordx2 v[102:103], v[40:41], off
	v_add_co_u32_e32 v40, vcc, 0x2a812000, v134
	s_nop 1
	v_addc_co_u32_e32 v41, vcc, 0, v135, vcc
	v_add_co_u32_e32 v42, vcc, 0x2a814000, v134
	s_nop 1
	v_addc_co_u32_e32 v43, vcc, 0, v135, vcc
	v_add_co_u32_e32 v44, vcc, 0x2a816000, v134
	s_nop 1
	v_addc_co_u32_e32 v45, vcc, 0, v135, vcc
	global_load_dwordx2 v[104:105], v[40:41], off
	global_load_dwordx2 v[106:107], v[42:43], off
	global_load_dwordx2 v[108:109], v[44:45], off

.LBB0_940:
	s_or_b64 exec, exec, s[18:19]
	v_mov_b32_e32 v56, s5
	v_add_f32_e32 v209, s4, v56
	s_add_i32 s4, 0, 0x12900
	v_add_u32_e32 v205, s4, v185
	ds_read_b128 v[56:59], v196
	ds_read_b128 v[60:63], v196 offset:16
	ds_read_b128 v[64:67], v205
	v_add_u32_e32 v72, 0xffffff90, v92
	v_add_u32_e32 v206, s4, v187
	s_waitcnt lgkmcnt(2)
	v_add_f32_e32 v68, v56, v57
	v_add_f32_e32 v70, v58, v59
	s_waitcnt lgkmcnt(1)
	v_add_f32_e32 v60, v60, v61
	v_add_f32_e32 v62, v62, v63
	s_waitcnt lgkmcnt(0)
	v_mov_b32_e32 v69, v64
	v_mov_b32_e32 v71, v65
	v_mov_b32_e32 v61, v66
	v_mov_b32_e32 v63, v67
	ds_read_b128 v[56:59], v197
	ds_read_b32 v66, v186
	v_pk_add_f32 v[64:65], v[68:69], v[70:71]
	v_pk_add_f32 v[60:61], v[60:61], v[62:63]
	v_and_b32_e32 v62, 0xffff0000, v116
	v_pk_add_f32 v[60:61], v[64:65], v[60:61]
	v_mul_f32_e32 v62, 0xbfb8aa3b, v62
	v_add_f32_e32 v60, v60, v61
	v_lshlrev_b32_e32 v61, 16, v116
	v_mul_f32_e32 v61, 0xbfb8aa3b, v61
	v_exp_f32_e32 v61, v61
	s_waitcnt lgkmcnt(0)
	v_mul_f32_e32 v66, 0xbfb8aa3b, v66
	v_exp_f32_e32 v63, v62
	v_exp_f32_e32 v66, v66
	v_add_f32_e32 v61, 1.0, v61
	v_lshlrev_b32_e32 v64, 16, v117
	v_rcp_f32_e32 v62, v61
	v_add_f32_e32 v61, 1.0, v63
	v_max_f32_e64 v60, |v60|, v66
	v_and_b32_e32 v65, 0xffff0000, v117
	v_rcp_f32_e32 v63, v61
	v_mul_f32_e32 v61, 0xbfb8aa3b, v64
	v_rcp_f32_e32 v60, v60
	v_exp_f32_e32 v61, v61
	v_mul_f32_e32 v64, 0xbfb8aa3b, v65
	v_exp_f32_e32 v65, v64
	ds_read_b32 v67, v188
	ds_read_b32 v68, v190
	ds_read_b32 v69, v192
	v_pk_mul_f32 v[52:53], v[52:53], v[60:61] op_sel_hi:[1,0]
	v_add_f32_e32 v61, 1.0, v61
	v_rcp_f32_e32 v64, v61
	v_add_f32_e32 v61, 1.0, v65
	v_rcp_f32_e32 v65, v61
	v_pk_mul_f32 v[54:55], v[54:55], v[60:61] op_sel_hi:[1,0]
	v_pk_mul_f32 v[52:53], v[62:63], v[52:53]
	ds_read_b128 v[60:63], v206
	v_pk_mul_f32 v[54:55], v[64:65], v[54:55]
	v_cvt_pk_bf16_f32 v52, v52, v53
	v_cvt_pk_bf16_f32 v53, v54, v55
	v_lshlrev_b64 v[54:55], 7, v[72:73]
	v_lshl_add_u64 v[54:55], v[76:77], 0, v[54:55]
	global_store_dwordx2 v[54:55], v[52:53], off
	ds_read_b128 v[52:55], v197 offset:16
	v_add_f32_e32 v56, v56, v57
	v_add_f32_e32 v58, v58, v59
	s_waitcnt lgkmcnt(1)
	v_mov_b32_e32 v57, v60
	v_mov_b32_e32 v59, v61
	s_waitcnt lgkmcnt(0)
	v_add_f32_e32 v52, v52, v53
	v_add_f32_e32 v54, v54, v55
	v_mov_b32_e32 v53, v62
	v_mov_b32_e32 v55, v63
	v_pk_add_f32 v[56:57], v[56:57], v[58:59]
	v_pk_add_f32 v[52:53], v[52:53], v[54:55]
	v_and_b32_e32 v54, 0xffff0000, v114
	v_pk_add_f32 v[52:53], v[56:57], v[52:53]
	v_mul_f32_e32 v54, 0xbfb8aa3b, v54
	v_add_f32_e32 v52, v52, v53
	v_lshlrev_b32_e32 v53, 16, v114
	v_mul_f32_e32 v53, 0xbfb8aa3b, v53
	v_exp_f32_e32 v53, v53
	v_mul_f32_e32 v58, 0xbfb8aa3b, v67
	v_exp_f32_e32 v55, v54
	v_exp_f32_e32 v58, v58
	v_add_f32_e32 v53, 1.0, v53
	v_lshlrev_b32_e32 v56, 16, v115
	v_rcp_f32_e32 v54, v53
	v_add_f32_e32 v53, 1.0, v55
	v_max_f32_e64 v52, |v52|, v58
	v_and_b32_e32 v57, 0xffff0000, v115
	v_rcp_f32_e32 v55, v53
	v_mul_f32_e32 v53, 0xbfb8aa3b, v56
	v_rcp_f32_e32 v52, v52
	v_exp_f32_e32 v53, v53
	v_mul_f32_e32 v56, 0xbfb8aa3b, v57
	v_exp_f32_e32 v57, v56
	v_add_u32_e32 v72, 0xffffffa0, v92
	v_pk_mul_f32 v[48:49], v[48:49], v[52:53] op_sel_hi:[1,0]
	v_add_f32_e32 v53, 1.0, v53
	v_rcp_f32_e32 v56, v53
	v_add_f32_e32 v53, 1.0, v57
	v_rcp_f32_e32 v57, v53
	v_pk_mul_f32 v[48:49], v[54:55], v[48:49]
	v_add_u32_e32 v207, s4, v189
	v_cvt_pk_bf16_f32 v54, v48, v49
	v_pk_mul_f32 v[48:49], v[50:51], v[52:53] op_sel_hi:[1,0]
	v_add_u32_e32 v208, s4, v191
	v_pk_mul_f32 v[48:49], v[56:57], v[48:49]
	ds_read_b128 v[56:59], v207
	v_cvt_pk_bf16_f32 v55, v48, v49
	v_lshlrev_b64 v[48:49], 7, v[72:73]
	v_lshl_add_u64 v[52:53], v[76:77], 0, v[48:49]
	ds_read_b128 v[48:51], v198
	global_store_dwordx2 v[52:53], v[54:55], off
	ds_read_b128 v[52:55], v198 offset:16
	s_waitcnt lgkmcnt(2)
	v_mov_b32_e32 v61, v56
	v_mov_b32_e32 v63, v57
	s_waitcnt lgkmcnt(1)
	v_add_f32_e32 v60, v48, v49
	v_add_f32_e32 v62, v50, v51
	s_waitcnt lgkmcnt(0)
	v_add_f32_e32 v52, v52, v53
	v_add_f32_e32 v54, v54, v55
	v_mov_b32_e32 v53, v58
	v_mov_b32_e32 v55, v59
	v_pk_add_f32 v[56:57], v[60:61], v[62:63]
	v_pk_add_f32 v[52:53], v[52:53], v[54:55]
	v_and_b32_e32 v54, 0xffff0000, v112
	v_pk_add_f32 v[52:53], v[56:57], v[52:53]
	v_mul_f32_e32 v54, 0xbfb8aa3b, v54
	v_add_f32_e32 v52, v52, v53
	v_lshlrev_b32_e32 v53, 16, v112
	v_mul_f32_e32 v53, 0xbfb8aa3b, v53
	v_exp_f32_e32 v53, v53
	v_mul_f32_e32 v58, 0xbfb8aa3b, v68
	v_exp_f32_e32 v55, v54
	v_exp_f32_e32 v58, v58
	v_add_f32_e32 v53, 1.0, v53
	v_lshlrev_b32_e32 v56, 16, v113
	v_rcp_f32_e32 v54, v53
	v_add_f32_e32 v53, 1.0, v55
	v_max_f32_e64 v52, |v52|, v58
	v_and_b32_e32 v57, 0xffff0000, v113
	v_rcp_f32_e32 v55, v53
	v_mul_f32_e32 v53, 0xbfb8aa3b, v56
	v_rcp_f32_e32 v52, v52
	v_exp_f32_e32 v53, v53
	v_mul_f32_e32 v56, 0xbfb8aa3b, v57
	v_exp_f32_e32 v57, v56
	v_add_u32_e32 v72, 0xffffffb0, v92
	v_pk_mul_f32 v[44:45], v[44:45], v[52:53] op_sel_hi:[1,0]
	v_add_f32_e32 v53, 1.0, v53
	v_rcp_f32_e32 v56, v53
	v_add_f32_e32 v53, 1.0, v57
	v_rcp_f32_e32 v57, v53
	v_pk_mul_f32 v[46:47], v[46:47], v[52:53] op_sel_hi:[1,0]
	v_pk_mul_f32 v[44:45], v[54:55], v[44:45]
	ds_read_b128 v[48:51], v199
	v_pk_mul_f32 v[46:47], v[56:57], v[46:47]
	v_cvt_pk_bf16_f32 v44, v44, v45
	v_cvt_pk_bf16_f32 v45, v46, v47
	v_lshlrev_b64 v[46:47], 7, v[72:73]
	v_lshl_add_u64 v[46:47], v[76:77], 0, v[46:47]
	global_store_dwordx2 v[46:47], v[44:45], off
	ds_read_b128 v[44:47], v199 offset:16
	ds_read_b128 v[52:55], v208
	s_waitcnt lgkmcnt(2)
	v_add_f32_e32 v48, v48, v49
	v_add_f32_e32 v50, v50, v51
	v_subrev_u32_e32 v72, 64, v92
	s_waitcnt lgkmcnt(1)
	v_add_f32_e32 v44, v44, v45
	v_add_f32_e32 v46, v46, v47
	s_waitcnt lgkmcnt(0)
	v_mov_b32_e32 v49, v52
	v_mov_b32_e32 v51, v53
	v_mov_b32_e32 v45, v54
	v_mov_b32_e32 v47, v55
	v_pk_add_f32 v[48:49], v[48:49], v[50:51]
	v_pk_add_f32 v[44:45], v[44:45], v[46:47]
	v_and_b32_e32 v46, 0xffff0000, v110
	v_pk_add_f32 v[44:45], v[48:49], v[44:45]
	v_mul_f32_e32 v46, 0xbfb8aa3b, v46
	v_add_f32_e32 v44, v44, v45
	v_lshlrev_b32_e32 v45, 16, v110
	v_mul_f32_e32 v45, 0xbfb8aa3b, v45
	v_exp_f32_e32 v45, v45
	v_mul_f32_e32 v50, 0xbfb8aa3b, v69
	v_exp_f32_e32 v47, v46
	v_exp_f32_e32 v50, v50
	v_add_f32_e32 v45, 1.0, v45
	v_lshlrev_b32_e32 v48, 16, v111
	v_rcp_f32_e32 v46, v45
	v_add_f32_e32 v45, 1.0, v47
	v_max_f32_e64 v44, |v44|, v50
	v_and_b32_e32 v49, 0xffff0000, v111
	v_rcp_f32_e32 v47, v45
	v_mul_f32_e32 v45, 0xbfb8aa3b, v48
	v_rcp_f32_e32 v44, v44
	v_exp_f32_e32 v45, v45
	v_mul_f32_e32 v48, 0xbfb8aa3b, v49
	v_exp_f32_e32 v49, v48
	s_waitcnt vmcnt(21)
	v_mov_b64_e32 v[116:117], v[98:99]
	v_mov_b64_e32 v[114:115], v[96:97]
	v_mov_b64_e32 v[112:113], v[80:81]
	v_mov_b64_e32 v[110:111], v[74:75]
	v_mov_b32_e32 v154, v100
	v_readlane_b32 s33, v158, 63
	v_pk_mul_f32 v[40:41], v[40:41], v[44:45] op_sel_hi:[1,0]
	v_add_f32_e32 v45, 1.0, v45
	v_rcp_f32_e32 v48, v45
	v_add_f32_e32 v45, 1.0, v49
	v_rcp_f32_e32 v49, v45
	v_pk_mul_f32 v[42:43], v[42:43], v[44:45] op_sel_hi:[1,0]
	v_pk_mul_f32 v[40:41], v[46:47], v[40:41]
	s_and_b64 vcc, exec, s[14:15]
	v_pk_mul_f32 v[42:43], v[48:49], v[42:43]
	v_cvt_pk_bf16_f32 v40, v40, v41
	v_cvt_pk_bf16_f32 v41, v42, v43
	v_lshlrev_b64 v[42:43], 7, v[72:73]
	v_lshl_add_u64 v[42:43], v[76:77], 0, v[42:43]
	global_store_dwordx2 v[42:43], v[40:41], off
	s_waitcnt lgkmcnt(0)
	s_barrier
	v_max_f32_e32 v40, v158, v158
	v_max_f32_e32 v40, v209, v40
	v_readlane_b32 s5, v159, 63
	v_readlane_b32 s4, v40, 63
	s_cbranch_vccnz .LBB0_942
	v_sub_f32_e32 v42, v209, v40
	v_mul_f32_e32 v42, 0x3fb8aa3b, v42
	v_exp_f32_e32 v42, v42
	v_add_f32_e32 v41, v159, v40
	ds_write_b32 v161, v157
	ds_write_b32 v162, v40
	ds_write_b32 v163, v41
	ds_write_b32 v164, v42
.LBB0_942:
	ds_write_b128 v166, v[12:15]
	ds_write_b128 v166, v[16:19] offset:9216
	ds_write_b128 v166, v[24:27] offset:18432
	ds_read_b128 v[40:43], v167
	ds_read_b128 v[44:47], v167 offset:16
	v_lshlrev_b32_e32 v52, 16, v12
	v_and_b32_e32 v53, 0xffff0000, v13
	v_and_b32_e32 v48, 0xffff0000, v12
	s_waitcnt lgkmcnt(1)
	v_mov_b32_e32 v50, v41
	v_mov_b32_e32 v41, v43
	v_lshlrev_b32_e32 v49, 16, v13
	v_mov_b32_e32 v51, v42
	v_pk_mul_f32 v[40:41], v[40:41], v[52:53]
	v_lshlrev_b32_e32 v43, 16, v15
	v_pk_fma_f32 v[40:41], v[50:51], v[48:49], v[40:41]
	s_waitcnt lgkmcnt(0)
	v_mov_b32_e32 v49, v46
	v_and_b32_e32 v51, 0xffff0000, v15
	v_and_b32_e32 v50, 0xffff0000, v14
	v_mov_b32_e32 v46, v45
	v_lshlrev_b32_e32 v42, 16, v14
	v_mov_b32_e32 v48, v44
	v_pk_mul_f32 v[44:45], v[46:47], v[50:51]
	v_add_f32_e32 v40, v40, v41
	v_pk_fma_f32 v[42:43], v[48:49], v[42:43], v[44:45]
	v_max_f32_e32 v44, v165, v165
	v_max_f32_e32 v45, v209, v209
	v_max_f32_e32 v44, v45, v44
	v_sub_f32_e32 v44, v209, v44
	v_mul_f32_e32 v44, 0x3fb8aa3b, v44
	v_exp_f32_e32 v44, v44
	v_add_f32_e32 v40, v42, v40
	v_add_f32_e32 v40, v43, v40
	s_andn2_b64 vcc, exec, s[74:75]
	v_mul_f32_e32 v40, v44, v40
	ds_write_b32 v168, v40
	ds_write_b128 v169, v[32:35] offset:27648
	ds_write_b128 v170, v[36:39] offset:27648
	s_cbranch_vccnz .LBB0_944
	v_add_co_u32_e32 v12, vcc, 0x51b92000, v146
	s_nop 1
	v_addc_co_u32_e32 v13, vcc, 0, v147, vcc
	v_add_co_u32_e32 v16, vcc, 0x51b94000, v146
	s_nop 1
	v_addc_co_u32_e32 v17, vcc, 0, v147, vcc
	v_add_co_u32_e32 v24, vcc, 0x51b96000, v146
	global_load_dwordx4 v[12:15], v[12:13], off offset:3072
	s_nop 0
	global_load_dwordx4 v[16:19], v[16:17], off offset:3072
	v_addc_co_u32_e32 v25, vcc, 0, v147, vcc
	v_add_co_u32_e32 v32, vcc, 0x51b98000, v144
	s_nop 1
	v_addc_co_u32_e32 v33, vcc, 0, v145, vcc
	global_load_dwordx4 v[24:27], v[24:25], off offset:3072
	s_nop 0
	global_load_dword v157, v[32:33], off offset:3072
	global_load_dword v158, v[32:33], off offset:3328
	global_load_dword v159, v[32:33], off offset:3584
	v_add_co_u32_e32 v32, vcc, 0x51b98000, v142
	s_nop 1
	v_addc_co_u32_e32 v33, vcc, 0, v143, vcc
	v_add_co_u32_e32 v34, vcc, 0x51b98000, v140
	s_nop 1
	v_addc_co_u32_e32 v35, vcc, 0, v141, vcc
	v_add_co_u32_e32 v36, vcc, 0x40818000, v138
	s_nop 1
	v_addc_co_u32_e32 v37, vcc, 0, v139, vcc
	global_load_dword v165, v[32:33], off offset:3328
	global_load_dword v100, v[34:35], off offset:3840
	s_nop 0
	global_load_dwordx4 v[32:35], v[36:37], off
	v_add_co_u32_e32 v36, vcc, 0x40818000, v136
	s_nop 1
	v_addc_co_u32_e32 v37, vcc, 0, v137, vcc
	v_add_co_u32_e32 v40, vcc, 0x2a818000, v134
	s_nop 1
	v_addc_co_u32_e32 v41, vcc, 0, v135, vcc
	global_load_dwordx4 v[36:39], v[36:37], off
	s_nop 0
	global_load_dwordx2 v[98:99], v[40:41], off
	v_add_co_u32_e32 v40, vcc, 0x2a81a000, v134
	s_nop 1
	v_addc_co_u32_e32 v41, vcc, 0, v135, vcc
	v_add_co_u32_e32 v42, vcc, 0x2a81c000, v134
	s_nop 1
	v_addc_co_u32_e32 v43, vcc, 0, v135, vcc
	v_add_co_u32_e32 v44, vcc, 0x2a81e000, v134
	s_nop 1
	v_addc_co_u32_e32 v45, vcc, 0, v135, vcc
	global_load_dwordx2 v[96:97], v[40:41], off
	global_load_dwordx2 v[80:81], v[42:43], off
	global_load_dwordx2 v[74:75], v[44:45], off

.LBB0_950:
	ds_read_b32 v72, v177
	s_nop 0
	ds_read_b128 v[68:71], v178
	ds_read_b128 v[134:137], v178 offset:64
	ds_read2_b32 v[66:67], v176 offset1:16
	s_waitcnt lgkmcnt(2)
	v_sub_f32_e32 v64, v68, v72
	v_mul_f32_e32 v64, 0x3fb8aa3b, v64
	v_exp_f32_e32 v68, v64
	s_waitcnt lgkmcnt(1)
	v_sub_f32_e32 v65, v134, v72
	v_mul_f32_e32 v64, 0x3fb8aa3b, v65
	v_exp_f32_e32 v93, v64
	v_mul_f32_e32 v60, v60, v68
	v_sub_f32_e32 v68, v69, v72
	v_mul_f32_e32 v68, 0x3fb8aa3b, v68
	v_exp_f32_e32 v69, v68
	v_sub_f32_e32 v68, v135, v72
	v_mul_f32_e32 v68, 0x3fb8aa3b, v68
	v_mul_f32_e32 v56, v56, v93
	v_exp_f32_e32 v93, v68
	v_cndmask_b32_e64 v68, v56, 0, s[28:29]
	v_mul_f32_e32 v56, v61, v69
	v_cndmask_b32_e64 v61, v56, 0, s[30:31]
	v_mul_f32_e32 v56, v57, v93
	v_sub_f32_e32 v57, v70, v72
	v_mul_f32_e32 v57, 0x3fb8aa3b, v57
	v_sub_f32_e32 v69, v136, v72
	v_exp_f32_e32 v57, v57
	v_mul_f32_e32 v69, 0x3fb8aa3b, v69
	v_exp_f32_e32 v70, v69
	v_cndmask_b32_e64 v69, v56, 0, s[34:35]
	v_mul_f32_e32 v56, v62, v57
	v_sub_f32_e32 v57, v71, v72
	v_cndmask_b32_e64 v62, v56, 0, s[36:37]
	v_mul_f32_e32 v56, v58, v70
	v_mul_f32_e32 v57, 0x3fb8aa3b, v57
	v_sub_f32_e32 v58, v137, v72
	v_exp_f32_e32 v57, v57
	v_mul_f32_e32 v58, 0x3fb8aa3b, v58
	v_exp_f32_e32 v58, v58
	v_cndmask_b32_e64 v70, v56, 0, s[38:39]
	v_mul_f32_e32 v56, v63, v57
	v_cndmask_b32_e64 v60, v60, 0, s[26:27]
	v_cndmask_b32_e64 v71, v56, 0, s[40:41]
	v_mul_f32_e32 v56, v59, v58
	v_cndmask_b32_e64 v63, v56, 0, s[42:43]
	v_add_f32_e32 v56, v60, v61
	v_add_f32_e32 v57, v62, v71
	v_add_f32_e32 v56, v56, v57
	v_add_f32_e32 v57, v68, v69
	v_add_f32_e32 v58, v70, v63
	v_add_f32_e32 v57, v57, v58
	ds_read2_b32 v[64:65], v176 offset0:32 offset1:48
	v_mov_b32_e32 v58, v56
	v_mov_b32_e32 v59, v57
	s_nop 0
	v_permlane16_swap_b32_e32 v56, v58
	v_permlane16_swap_b32_e32 v57, v59
	v_add_f32_e32 v56, v56, v58
	v_add_f32_e32 v57, v57, v59
	v_mov_b32_e32 v58, v56
	v_mov_b32_e32 v59, v57
	s_nop 0
	v_permlane32_swap_b32_e32 v56, v58
	v_permlane32_swap_b32_e32 v57, v59
	s_and_saveexec_b64 s[10:11], s[8:9]
	v_pk_add_f32 v[56:57], v[56:57], v[58:59]
	ds_write_b64 v179, v[56:57]
	s_or_b64 exec, exec, s[10:11]
	v_cvt_pk_bf16_f32 v56, v60, v61
	v_cvt_pk_bf16_f32 v57, v62, v71
	v_cvt_pk_bf16_f32 v58, v68, v69
	v_cvt_pk_bf16_f32 v59, v70, v63
	ds_write2_b64 v204, v[56:57], v[58:59] offset1:4
	s_waitcnt lgkmcnt(0)
	s_barrier
	ds_read_b64_tr_b16 v[56:57], v194 offset:27648
	ds_read_b64_tr_b16 v[58:59], v194 offset:28736
	s_waitcnt lgkmcnt(4)
	v_pk_mul_f32 v[54:55], v[54:55], v[66:67] op_sel_hi:[1,0]
	v_pk_mul_f32 v[52:53], v[52:53], v[66:67] op_sel_hi:[1,0]
	v_mov_b32_e32 v66, v67
	ds_read_b128 v[60:63], v182
	v_pk_mul_f32 v[50:51], v[50:51], v[66:67] op_sel_hi:[1,0]
	v_pk_mul_f32 v[48:49], v[48:49], v[66:67] op_sel_hi:[1,0]
	ds_read_b128 v[66:69], v182 offset:2304
	ds_read_b64_tr_b16 v[70:71], v194 offset:37440
	s_waitcnt lgkmcnt(2)
	v_mfma_f32_16x16x32_bf16 v[52:55], v[56:59], v[60:63], v[52:55]
	v_mul_f32_e64 v46, v46, v64
	v_mul_f32_e64 v47, v47, v64
	v_pk_mul_f32 v[44:45], v[44:45], v[64:65] op_sel_hi:[1,0]
	ds_read_b128 v[60:63], v182 offset:4608
	s_waitcnt lgkmcnt(2)
	v_mfma_f32_16x16x32_bf16 v[48:51], v[56:59], v[66:69], v[48:51]
	v_mov_b32_e32 v68, v65
	ds_read_b128 v[64:67], v182 offset:6912
	v_pk_mul_f32 v[42:43], v[42:43], v[68:69] op_sel_hi:[1,0]
	v_pk_mul_f32 v[40:41], v[40:41], v[68:69] op_sel_hi:[1,0]
	s_waitcnt lgkmcnt(1)
	v_mfma_f32_16x16x32_bf16 v[44:47], v[56:59], v[60:63], v[44:47]
	ds_read_b64_tr_b16 v[62:63], v195 offset:19008
	ds_read_b64_tr_b16 v[60:61], v195 offset:18432
	s_waitcnt lgkmcnt(2)
	v_mfma_f32_16x16x32_bf16 v[40:43], v[56:59], v[64:67], v[40:43]
	ds_read_b64_tr_b16 v[66:67], v195 offset:19040
	ds_read_b64_tr_b16 v[64:65], v195 offset:18464
	ds_read_b64_tr_b16 v[134:135], v195 offset:18496
	ds_read_b64_tr_b16 v[138:139], v195 offset:18528
	ds_read_b64_tr_b16 v[136:137], v195 offset:19072
	ds_read_b64_tr_b16 v[140:141], v195 offset:19104
	ds_read_b64_tr_b16 v[68:69], v194 offset:36352
	s_waitcnt lgkmcnt(7)
	v_mfma_f32_16x16x32_bf16 v[60:63], v[60:63], v[56:59], 0
	s_waitcnt lgkmcnt(5)
	v_mfma_f32_16x16x32_bf16 v[64:67], v[64:67], v[56:59], 0
	s_waitcnt lgkmcnt(2)
	v_mfma_f32_16x16x32_bf16 v[134:137], v[134:137], v[56:59], 0
	s_waitcnt lgkmcnt(1)
	v_mfma_f32_16x16x32_bf16 v[138:141], v[138:141], v[56:59], 0
	ds_read_b128 v[56:59], v183 offset:4608
	ds_read_b128 v[142:145], v183 offset:6912
	s_waitcnt lgkmcnt(1)
	v_mfma_f32_16x16x32_bf16 v[44:47], v[68:71], v[56:59], v[44:47]
	ds_read_b64_tr_b16 v[56:57], v195 offset:23040
	ds_read_b64_tr_b16 v[58:59], v195 offset:23616
	s_waitcnt lgkmcnt(0)
	v_mfma_f32_16x16x32_bf16 v[60:63], v[56:59], v[68:71], v[60:63]
	v_mov_b32_e32 v56, s4
	v_sub_f32_e32 v56, s33, v56
	v_mul_f32_e32 v56, 0x3fb8aa3b, v56
	v_subrev_f32_e32 v57, s4, v209
	v_mfma_f32_16x16x32_bf16 v[40:43], v[68:71], v[142:145], v[40:43]
	ds_read_b64_tr_b16 v[144:145], v195 offset:23648
	ds_read_b64_tr_b16 v[142:143], v195 offset:23072
	ds_read_b64_tr_b16 v[210:211], v195 offset:23104
	ds_read_b64_tr_b16 v[214:215], v195 offset:23136
	ds_read_b64_tr_b16 v[212:213], v195 offset:23680
	ds_read_b64_tr_b16 v[216:217], v195 offset:23712
	v_exp_f32_e32 v56, v56
	v_mul_f32_e32 v57, 0x3fb8aa3b, v57
	s_waitcnt lgkmcnt(4)
	v_mfma_f32_16x16x32_bf16 v[64:67], v[142:145], v[68:71], v[64:67]
	v_exp_f32_e32 v58, v57
	v_pk_mul_f32 v[62:63], v[56:57], v[62:63] op_sel_hi:[0,1]
	v_pk_mul_f32 v[60:61], v[56:57], v[60:61] op_sel_hi:[0,1]
	s_waitcnt lgkmcnt(1)
	v_mfma_f32_16x16x32_bf16 v[134:137], v[210:213], v[68:71], v[134:137]
	v_fma_f32 v126, v126, v58, v62
	v_fma_f32 v127, v127, v58, v63
	s_nop 0
	v_pk_mul_f32 v[62:63], v[56:57], v[66:67] op_sel_hi:[0,1]
	v_pk_mul_f32 v[64:65], v[56:57], v[64:65] op_sel_hi:[0,1]
	s_waitcnt lgkmcnt(0)
	v_mfma_f32_16x16x32_bf16 v[68:71], v[214:217], v[68:71], v[138:141]
	v_fma_f32 v118, v118, v58, v60
	v_fma_f32 v119, v119, v58, v61
	v_pk_fma_f32 v[128:129], v[128:129], v[58:59], v[62:63] op_sel_hi:[1,0,1]
	v_pk_fma_f32 v[120:121], v[120:121], v[58:59], v[64:65] op_sel_hi:[1,0,1]
	v_cvt_pk_bf16_f32 v60, v118, v119
	v_cvt_pk_bf16_f32 v61, v126, v127
	v_cvt_pk_bf16_f32 v62, v120, v121
	v_cvt_pk_bf16_f32 v63, v128, v129
	ds_write2_b64 v101, v[60:61], v[62:63] offset1:4
	v_pk_mul_f32 v[62:63], v[56:57], v[134:135] op_sel_hi:[0,1]
	v_pk_mul_f32 v[60:61], v[56:57], v[136:137] op_sel_hi:[0,1]
	v_pk_fma_f32 v[122:123], v[122:123], v[58:59], v[62:63] op_sel_hi:[1,0,1]
	v_pk_mul_f32 v[62:63], v[56:57], v[70:71] op_sel_hi:[0,1]
	v_pk_mul_f32 v[64:65], v[56:57], v[68:69] op_sel_hi:[0,1]
	v_pk_fma_f32 v[130:131], v[130:131], v[58:59], v[60:61] op_sel_hi:[1,0,1]
	v_pk_fma_f32 v[132:133], v[132:133], v[58:59], v[62:63] op_sel_hi:[1,0,1]
	v_pk_fma_f32 v[124:125], v[124:125], v[58:59], v[64:65] op_sel_hi:[1,0,1]
	v_cvt_pk_bf16_f32 v60, v122, v123
	v_cvt_pk_bf16_f32 v61, v130, v131
	v_cvt_pk_bf16_f32 v62, v124, v125
	v_cvt_pk_bf16_f32 v63, v132, v133
	ds_write2_b64 v101, v[60:61], v[62:63] offset0:8 offset1:12
	s_and_saveexec_b64 s[10:11], s[6:7]
	s_cbranch_execz .LBB0_925
	ds_read_b32 v57, v184
	v_mov_b32_e32 v155, v58
	s_waitcnt lgkmcnt(0)
	v_pk_mul_f32 v[56:57], v[154:155], v[56:57]
	s_nop 0
	v_add_f32_e32 v56, v56, v57
	ds_write_b32 v184, v56
	s_branch .LBB0_925

.LBB0_2183:
	s_or_b64 exec, exec, s[8:9]
	s_sub_i32 s2, s75, 32
	s_lshr_b32 s3, s2, 2
	s_lshl_b32 s2, s75, 7
	s_lshl_b32 s8, s3, 13
	s_and_b32 s4, s2, 0x180
	s_lshl_b32 s3, s3, 9
	s_or_b32 s3, s3, s4
	s_lshl_b32 s2, s74, 4
	s_mul_i32 s10, s3, 0x6400
	s_add_u32 s18, s89, s10
	v_ashrrev_i32_e32 v151, 31, v150
	v_ashrrev_i32_e32 v43, 4, v148
	s_addc_u32 s19, s90, 0
	v_lshlrev_b64 v[40:41], 4, v[150:151]
	v_lshlrev_b32_e32 v69, 2, v43
	v_lshl_add_u64 v[24:25], s[18:19], 0, v[40:41]
	s_movk_i32 s3, 0x2000
	v_add_u32_e32 v0, s2, v69
	v_add_co_u32_e32 v4, vcc, s3, v24
	v_add_u32_e32 v70, s4, v0
	s_nop 0
	v_addc_co_u32_e32 v5, vcc, 0, v25, vcc
	s_movk_i32 s4, 0x4000
	s_add_u32 s20, s18, 0x6000
	v_ashrrev_i32_e32 v149, 31, v148
	v_lshlrev_b32_e32 v1, 15, v70
	v_and_b32_e32 v0, 60, v0
	s_mov_b32 s5, 0xffe00000
	v_add_co_u32_e32 v8, vcc, s4, v24
	s_addc_u32 s21, s19, 0
	v_lshlrev_b64 v[44:45], 2, v[148:149]
	s_mov_b32 s16, 0
	v_and_or_b32 v0, v1, s5, v0
	v_addc_co_u32_e32 v9, vcc, 0, v25, vcc
	v_lshl_add_u64 v[12:13], s[20:21], 0, v[44:45]
	v_ashrrev_i32_e32 v54, 3, v150
	v_ashrrev_i32_e32 v152, 4, v150
	s_mov_b32 s9, s16
	v_add_u32_e32 v42, 0x3000000, v0
	global_load_dwordx4 v[0:3], v[24:25], off
	s_nop 0
	global_load_dwordx4 v[4:7], v[4:5], off
	s_nop 0
	global_load_dwordx4 v[8:11], v[8:9], off
	s_nop 0
	global_load_dword v149, v[12:13], off
	global_load_dword v151, v[12:13], off offset:256
	global_load_dword v156, v[12:13], off offset:512
	v_ashrrev_i32_e32 v55, 31, v54
	v_and_b32_e32 v12, 63, v148
	v_ashrrev_i32_e32 v153, 31, v152
	v_lshlrev_b64 v[46:47], 2, v[54:55]
	v_lshlrev_b32_e32 v55, 2, v12
	v_lshl_add_u64 v[12:13], s[8:9], 0, v[152:153]
	s_lshl_b32 s5, s75, 23
	v_lshlrev_b64 v[48:49], 9, v[12:13]
	s_and_b32 s12, s5, 0x1000000
	v_lshl_add_u64 v[12:13], s[60:61], 0, v[48:49]
	s_or_b32 s22, s12, 0x16000000
	s_mov_b32 s23, s16
	s_lshl_b32 s5, s75, 8
	v_lshlrev_b32_e32 v14, 3, v148
	v_lshl_add_u64 v[12:13], v[12:13], 0, s[22:23]
	s_and_b32 s14, s5, 0x100
	s_mov_b32 s15, s16
	v_and_b32_e32 v180, 0x78, v14
	v_mov_b32_e32 v73, 0
	v_lshl_add_u64 v[12:13], v[12:13], 0, s[14:15]
	v_lshlrev_b32_e32 v72, 1, v180
	v_lshl_add_u64 v[30:31], v[12:13], 0, v[72:73]
	v_add_u32_e32 v12, 0x200, v150
	v_ashrrev_i32_e32 v56, 4, v12
	v_ashrrev_i32_e32 v57, 31, v56
	v_and_b32_e32 v68, 15, v148
	v_add_u32_e32 v16, 0x1800, v70
	v_lshl_add_u64 v[12:13], s[8:9], 0, v[56:57]
	v_lshlrev_b64 v[52:53], 9, v[12:13]
	v_or_b32_e32 v50, s8, v68
	v_mov_b32_e32 v51, v73
	v_ashrrev_i32_e32 v16, 8, v16
	v_lshl_add_u64 v[12:13], s[60:61], 0, v[52:53]
	v_lshlrev_b64 v[58:59], 9, v[50:51]
	v_ashrrev_i32_e32 v17, 31, v16
	v_lshl_add_u64 v[12:13], v[12:13], 0, s[22:23]
	v_lshl_add_u64 v[14:15], s[60:61], 0, v[58:59]
	v_and_b32_e32 v18, 0xfc, v70
	v_lshlrev_b64 v[60:61], 24, v[16:17]
	v_lshl_add_u64 v[12:13], v[12:13], 0, s[14:15]
	v_lshl_add_u64 v[14:15], v[14:15], 0, v[60:61]
	v_lshlrev_b32_e32 v36, 1, v18
	v_mov_b32_e32 v37, v73
	v_lshl_add_u64 v[12:13], v[12:13], 0, v[72:73]
	v_lshl_add_u64 v[62:63], v[14:15], 0, v[36:37]
	global_load_dwordx4 v[20:23], v[12:13], off
	global_load_dwordx2 v[102:103], v[62:63], off
	v_add_co_u32_e32 v12, vcc, s3, v62
	s_movk_i32 s3, 0x6000
	s_nop 0
	v_addc_co_u32_e32 v13, vcc, 0, v63, vcc
	v_add_co_u32_e32 v14, vcc, s4, v62
	s_add_u32 s4, s18, 0xc400
	s_nop 0
	v_addc_co_u32_e32 v15, vcc, 0, v63, vcc
	v_add_co_u32_e32 v16, vcc, s3, v62
	s_addc_u32 s5, s19, 0
	s_nop 0
	v_addc_co_u32_e32 v17, vcc, 0, v63, vcc
	global_load_dwordx2 v[104:105], v[12:13], off
	global_load_dwordx2 v[106:107], v[14:15], off
	global_load_dwordx2 v[108:109], v[16:17], off
	v_add_co_u32_e32 v12, vcc, s3, v24
	s_mov_b32 s3, 0x8000
	s_nop 0
	v_addc_co_u32_e32 v13, vcc, 0, v25, vcc
	v_add_co_u32_e32 v16, vcc, s3, v24
	s_mov_b32 s3, 0xa000
	s_nop 0
	v_addc_co_u32_e32 v17, vcc, 0, v25, vcc
	v_add_co_u32_e32 v24, vcc, s3, v24
	v_lshl_add_u64 v[28:29], s[20:21], 0, v[46:47]
	s_nop 0
	v_addc_co_u32_e32 v25, vcc, 0, v25, vcc
	v_lshl_add_u64 v[32:33], s[4:5], 0, v[44:45]
	global_load_dwordx4 v[12:15], v[12:13], off offset:1024
	s_nop 0
	global_load_dwordx4 v[16:19], v[16:17], off offset:1024
	s_nop 0
	global_load_dwordx4 v[24:27], v[24:25], off offset:1024
	s_nop 0
	global_load_dword v157, v[32:33], off
	global_load_dword v158, v[32:33], off offset:256
	global_load_dword v159, v[32:33], off offset:512
	v_lshl_add_u64 v[32:33], s[4:5], 0, v[46:47]
	global_load_dword v160, v[28:29], off offset:256
	global_load_dword v203, v55, s[20:21] offset:768
	s_nop 0
	global_load_dwordx4 v[28:31], v[30:31], off
	s_nop 0
	global_load_dword v100, v55, s[4:5] offset:768
	s_or_b32 s4, s8, 64
	s_mov_b32 s5, s16
	v_lshl_add_u64 v[34:35], s[4:5], 0, v[152:153]
	v_lshl_add_u64 v[38:39], s[4:5], 0, v[56:57]
	v_lshlrev_b64 v[34:35], 9, v[34:35]
	v_lshlrev_b64 v[38:39], 9, v[38:39]
	v_lshl_add_u64 v[34:35], s[60:61], 0, v[34:35]
	v_lshl_add_u64 v[38:39], s[60:61], 0, v[38:39]
	v_lshl_add_u64 v[34:35], v[34:35], 0, s[22:23]
	v_lshl_add_u64 v[38:39], v[38:39], 0, s[22:23]
	v_lshl_add_u64 v[34:35], v[34:35], 0, s[14:15]
	v_lshl_add_u64 v[38:39], v[38:39], 0, s[14:15]
	v_lshl_add_u64 v[34:35], v[34:35], 0, v[72:73]
	v_lshl_add_u64 v[38:39], v[38:39], 0, v[72:73]
	v_or_b32_e32 v72, s4, v68
	v_lshlrev_b64 v[64:65], 9, v[72:73]
	v_lshl_add_u64 v[64:65], s[60:61], 0, v[64:65]
	v_lshl_add_u64 v[64:65], v[64:65], 0, v[60:61]
	v_lshl_add_u64 v[64:65], v[64:65], 0, v[36:37]
	global_load_dword v165, v[32:33], off offset:256
	s_nop 0
	global_load_dwordx4 v[32:35], v[34:35], off
	s_nop 0
	global_load_dwordx4 v[36:39], v[38:39], off
	s_nop 0
	global_load_dwordx2 v[98:99], v[64:65], off
	v_add_co_u32_e32 v64, vcc, s3, v62
	s_mov_b32 s3, 0xc000
	s_nop 0
	v_addc_co_u32_e32 v65, vcc, 0, v63, vcc
	v_add_co_u32_e32 v66, vcc, s3, v62
	s_mov_b32 s3, 0xe000
	s_nop 0
	v_addc_co_u32_e32 v67, vcc, 0, v63, vcc
	v_add_co_u32_e32 v62, vcc, s3, v62
	s_cmp_eq_u32 s74, 0
	s_nop 0
	v_addc_co_u32_e32 v63, vcc, 0, v63, vcc
	global_load_dwordx2 v[96:97], v[64:65], off
	global_load_dwordx2 v[80:81], v[66:67], off
	global_load_dwordx2 v[74:75], v[62:63], off
	s_cselect_b64 s[20:21], -1, 0
	v_lshlrev_b32_e32 v51, 2, v148
	s_add_i32 s3, 0, 0x11c00
	s_add_i32 s13, 0, 0x11d00
	s_add_i32 s15, 0, 0x11e00
	s_add_i32 s17, 0, 0x11f00
	v_add_u32_e32 v161, s3, v51
	v_add_u32_e32 v162, s13, v51
	v_add_u32_e32 v163, s15, v51
	v_add_u32_e32 v164, s17, v51
	v_lshlrev_b32_e32 v51, 3, v150
	v_and_b32_e32 v51, 56, v51
	s_movk_i32 s18, 0x90
	v_mul_lo_u32 v54, v54, s18
	v_lshlrev_b32_e32 v57, 1, v51
	v_readlane_b32 s45, v250, 16
	v_add3_u32 v166, 0, v54, v57
	v_and_b32_e32 v54, 7, v148
	v_lshl_add_u32 v167, v51, 2, s45
	v_and_b32_e32 v51, 0x3ffffff8, v150
	s_add_i32 s19, 0, 0x12100
	v_lshlrev_b32_e32 v51, 2, v51
	v_lshlrev_b32_e32 v54, 2, v54
	s_lshl_b32 s4, s74, 1
	v_add3_u32 v168, s19, v51, v54
	s_movk_i32 s33, 0x110
	v_lshlrev_b32_e32 v54, 4, v150
	s_ashr_i32 s26, s74, 1
	s_and_b32 s44, s4, 2
	v_mul_lo_u32 v51, v152, s33
	v_and_b32_e32 v54, 0xf0, v54
	s_cmp_le_i32 s44, s26
	v_add3_u32 v169, 0, v51, v54
	v_mul_lo_u32 v51, v56, s33
	s_cselect_b64 s[22:23], -1, 0
	s_cmp_gt_i32 s44, s26
	v_add3_u32 v170, 0, v51, v54
	s_cselect_b64 s[4:5], -1, 0
	s_cmp_lt_i32 s44, s26
	v_mul_u32_u24_e32 v51, 0x90, v68
	v_lshlrev_b32_e32 v171, 3, v43
	v_and_b32_e32 v43, -16, v148
	s_cselect_b64 s[24:25], -1, 0
	s_cmp_ge_i32 s44, s26
	v_add3_u32 v172, 0, v51, v43
	v_or_b32_e32 v51, s2, v68
	s_cselect_b64 s[8:9], -1, 0
	v_mul_lo_u32 v51, v51, s18
	s_lshl_b32 s27, s44, 4
	v_add_u32_e32 v173, 0, v51
	v_or_b32_e32 v51, s27, v68
	v_mul_u32_u24_e32 v51, 0x90, v51
	v_add3_u32 v175, 0, v51, v43
	v_lshlrev_b32_e32 v51, 2, v68
	v_add_u32_e32 v176, s17, v51
	s_lshl_b32 s17, s26, 6
	s_add_i32 s13, s13, s17
	v_add_u32_e32 v177, s13, v51
	s_lshl_b32 s13, s44, 6
	s_add_i32 s3, s3, s13
	v_add_u32_e32 v174, v173, v43
	v_add_u32_e32 v178, s3, v43
	v_add_u32_e32 v43, s27, v69
	v_lshl_or_b32 v56, s26, 4, v68
	v_add_u32_e32 v57, 16, v43
	v_cmp_gt_i32_e32 vcc, v43, v56
	s_mul_i32 s2, s26, 0x900
	s_or_b64 s[26:27], s[4:5], vcc
	v_cmp_gt_i32_e32 vcc, v57, v56
	s_or_b64 s[28:29], s[8:9], vcc
	v_cmp_ge_i32_e32 vcc, v43, v56
	s_or_b64 s[30:31], s[4:5], vcc
	v_cmp_ge_i32_e32 vcc, v57, v56
	v_or_b32_e32 v57, 2, v43
	s_lshl_b32 s3, s44, 2
	s_or_b64 s[34:35], s[8:9], vcc
	v_cmp_gt_i32_e32 vcc, v57, v56
	v_add_u32_e32 v57, 18, v43
	s_add_i32 s3, s3, 0
	s_or_b64 s[36:37], s[4:5], vcc
	v_cmp_gt_i32_e32 vcc, v57, v56
	v_or_b32_e32 v57, 3, v43
	s_add_i32 s3, s3, 0x12900
	s_or_b64 s[38:39], s[8:9], vcc
	v_cmp_gt_i32_e32 vcc, v57, v56
	v_add_u32_e32 v43, 19, v43
	v_lshl_add_u32 v179, v56, 4, s3
	s_lshl_b32 s3, s44, 5
	s_or_b64 s[40:41], s[4:5], vcc
	v_cmp_gt_i32_e32 vcc, v43, v56
	v_mul_lo_u32 v43, v56, s18
	s_add_i32 s3, s3, 0
	v_add_u32_e32 v56, s3, v43
	v_ashrrev_i32_e32 v43, 1, v148
	v_bfe_u32 v202, v148, 2, 2
	v_and_or_b32 v43, v43, -8, v202
	v_mul_lo_u32 v63, v43, s33
	v_mul_lo_u32 v64, v43, s18
	v_ashrrev_i32_e32 v43, 31, v42
	v_lshl_add_u64 v[76:77], v[42:43], 1, s[64:65]
	v_or_b32_e32 v42, 16, v68
	s_lshl_b32 s3, s74, 5
	v_and_b32_e32 v201, 12, v200
	v_lshlrev_b32_e32 v43, 5, v42
	v_lshlrev_b32_e32 v187, 4, v42
	v_lshl_add_u32 v188, v42, 2, s15
	v_or_b32_e32 v42, 32, v68
	s_waitcnt vmcnt(0) lgkmcnt(0)
	s_barrier
	s_add_i32 s3, s3, 0
	v_lshlrev_b32_e32 v57, 1, v201
	v_add_u32_e32 v186, s15, v51
	v_lshlrev_b32_e32 v51, 5, v42
	v_lshlrev_b32_e32 v189, 4, v42
	v_lshl_add_u32 v190, v42, 2, s15
	v_or_b32_e32 v42, 48, v68
	s_mov_b32 s13, s16
	s_mov_b32 s11, s16
	v_add_u32_e32 v62, s3, v57
	v_add_u32_e32 v57, 0, v57
	v_lshlrev_b32_e32 v65, 5, v68
	v_lshlrev_b32_e32 v66, 5, v42
	v_lshlrev_b32_e32 v191, 4, v42
	v_lshl_add_u32 v192, v42, 2, s15
	v_lshl_add_u64 v[78:79], v[60:61], 0, v[58:59]
	v_lshlrev_b32_e32 v42, 1, v70
	s_movk_i32 s3, 0x1f8
	v_lshl_add_u64 v[82:83], s[12:13], 0, v[52:53]
	v_lshl_add_u64 v[84:85], s[12:13], 0, v[48:49]
	v_or_b32_e32 v72, s10, v55
	v_mov_b32_e32 v181, v73
	s_or_b64 s[42:43], s[8:9], vcc
	v_cmp_gt_u32_e64 s[8:9], 16, v148
	v_add_u32_e32 v182, 0xf800, v172
	v_add_u32_e32 v183, 0xf840, v172
	v_lshl_add_u32 v184, v150, 2, s45
	v_lshlrev_b32_e32 v185, 4, v68
	v_and_or_b32 v78, v42, s3, v78
	v_or3_b32 v82, v82, s14, v54
	v_or3_b32 v84, v84, s14, v54
	v_lshl_add_u64 v[86:87], v[40:41], 0, s[10:11]
	v_lshl_add_u64 v[88:89], v[44:45], 0, s[10:11]
	v_lshl_add_u64 v[90:91], v[46:47], 0, s[10:11]
	v_or_b32_e32 v92, 0x70, v50
	s_mov_b64 s[44:45], 0x10000
	s_mov_b64 s[46:47], 0xc800
	v_add_u32_e32 v193, v56, v171
	v_add_u32_e32 v194, v62, v63
	v_add_u32_e32 v195, v57, v64
	v_add_u32_e32 v196, s19, v65
	v_add_u32_e32 v197, s19, v43
	v_add_u32_e32 v198, s19, v51
	v_add_u32_e32 v199, s19, v66
	v_mov_b64_e32 v[94:95], v[72:73]
	v_mov_b32_e32 v101, 0
	s_mov_b32 s3, 0
	v_mov_b32_e32 v118, v73
	v_mov_b32_e32 v119, v73
	v_mov_b32_e32 v126, v73
	v_mov_b32_e32 v127, v73
	v_mov_b32_e32 v120, v73
	v_mov_b32_e32 v121, v73
	v_mov_b32_e32 v128, v73
	v_mov_b32_e32 v129, v73
	v_mov_b32_e32 v122, v73
	v_mov_b32_e32 v123, v73
	v_mov_b32_e32 v130, v73
	v_mov_b32_e32 v131, v73
	v_mov_b32_e32 v124, v73
	v_mov_b32_e32 v125, v73
	v_mov_b32_e32 v132, v73
	v_mov_b32_e32 v133, v73
	s_branch .LBB0_2185
.LBB0_2184:
	s_or_b64 exec, exec, s[10:11]
	ds_read_b128 v[56:59], v196
	ds_read_b128 v[60:63], v196 offset:16
	ds_read_b128 v[64:67], v205
	v_mov_b32_e32 v68, s5
	v_add_f32_e32 v101, s4, v68
	v_subrev_u32_e32 v72, 48, v92
	s_waitcnt lgkmcnt(2)
	v_add_f32_e32 v68, v56, v57
	v_add_f32_e32 v70, v58, v59
	s_waitcnt lgkmcnt(1)
	v_add_f32_e32 v60, v60, v61
	v_add_f32_e32 v62, v62, v63
	s_waitcnt lgkmcnt(0)
	v_mov_b32_e32 v69, v64
	v_mov_b32_e32 v71, v65
	v_mov_b32_e32 v61, v66
	v_mov_b32_e32 v63, v67
	ds_read_b128 v[56:59], v197
	ds_read_b32 v66, v186
	v_pk_add_f32 v[64:65], v[68:69], v[70:71]
	v_pk_add_f32 v[60:61], v[60:61], v[62:63]
	v_and_b32_e32 v62, 0xffff0000, v116
	v_pk_add_f32 v[60:61], v[64:65], v[60:61]
	v_mul_f32_e32 v62, 0xbfb8aa3b, v62
	v_add_f32_e32 v60, v60, v61
	v_lshlrev_b32_e32 v61, 16, v116
	v_mul_f32_e32 v61, 0xbfb8aa3b, v61
	v_exp_f32_e32 v61, v61
	s_waitcnt lgkmcnt(0)
	v_mul_f32_e32 v66, 0xbfb8aa3b, v66
	v_exp_f32_e32 v63, v62
	v_exp_f32_e32 v66, v66
	v_add_f32_e32 v61, 1.0, v61
	v_lshlrev_b32_e32 v64, 16, v117
	v_rcp_f32_e32 v62, v61
	v_add_f32_e32 v61, 1.0, v63
	v_max_f32_e64 v60, |v60|, v66
	v_and_b32_e32 v65, 0xffff0000, v117
	v_rcp_f32_e32 v63, v61
	v_mul_f32_e32 v61, 0xbfb8aa3b, v64
	v_rcp_f32_e32 v60, v60
	v_exp_f32_e32 v61, v61
	v_mul_f32_e32 v64, 0xbfb8aa3b, v65
	v_exp_f32_e32 v65, v64
	ds_read_b32 v67, v188
	ds_read_b32 v68, v190
	ds_read_b32 v69, v192
	v_pk_mul_f32 v[52:53], v[52:53], v[60:61] op_sel_hi:[1,0]
	v_add_f32_e32 v61, 1.0, v61
	v_rcp_f32_e32 v64, v61
	v_add_f32_e32 v61, 1.0, v65
	v_rcp_f32_e32 v65, v61
	v_pk_mul_f32 v[52:53], v[62:63], v[52:53]
	v_add_f32_e32 v56, v56, v57
	v_cvt_pk_bf16_f32 v62, v52, v53
	v_pk_mul_f32 v[52:53], v[54:55], v[60:61] op_sel_hi:[1,0]
	v_add_f32_e32 v58, v58, v59
	v_pk_mul_f32 v[52:53], v[64:65], v[52:53]
	v_mov_b32_e32 v93, v73
	v_cvt_pk_bf16_f32 v63, v52, v53
	v_lshlrev_b64 v[52:53], 7, v[72:73]
	v_lshl_add_u64 v[60:61], v[76:77], 0, v[52:53]
	ds_read_b128 v[52:55], v197 offset:16
	global_store_dwordx2 v[60:61], v[62:63], off
	ds_read_b128 v[60:63], v206
	v_subrev_u32_e32 v72, 32, v92
	s_add_i32 s3, s3, 2
	s_waitcnt lgkmcnt(1)
	v_add_f32_e32 v52, v52, v53
	v_add_f32_e32 v54, v54, v55
	s_waitcnt lgkmcnt(0)
	v_mov_b32_e32 v57, v60
	v_mov_b32_e32 v59, v61
	v_mov_b32_e32 v53, v62
	v_mov_b32_e32 v55, v63
	v_pk_add_f32 v[56:57], v[56:57], v[58:59]
	v_pk_add_f32 v[52:53], v[52:53], v[54:55]
	v_and_b32_e32 v54, 0xffff0000, v114
	v_pk_add_f32 v[52:53], v[56:57], v[52:53]
	v_mul_f32_e32 v54, 0xbfb8aa3b, v54
	v_add_f32_e32 v52, v52, v53
	v_lshlrev_b32_e32 v53, 16, v114
	v_mul_f32_e32 v53, 0xbfb8aa3b, v53
	v_exp_f32_e32 v53, v53
	v_mul_f32_e32 v58, 0xbfb8aa3b, v67
	v_exp_f32_e32 v55, v54
	v_exp_f32_e32 v58, v58
	v_add_f32_e32 v53, 1.0, v53
	v_lshlrev_b32_e32 v56, 16, v115
	v_rcp_f32_e32 v54, v53
	v_add_f32_e32 v53, 1.0, v55
	v_max_f32_e64 v52, |v52|, v58
	v_and_b32_e32 v57, 0xffff0000, v115
	v_rcp_f32_e32 v55, v53
	v_mul_f32_e32 v53, 0xbfb8aa3b, v56
	v_rcp_f32_e32 v52, v52
	v_exp_f32_e32 v53, v53
	v_mul_f32_e32 v56, 0xbfb8aa3b, v57
	v_exp_f32_e32 v57, v56
	v_lshl_add_u64 v[78:79], v[78:79], 0, s[44:45]
	v_pk_mul_f32 v[48:49], v[48:49], v[52:53] op_sel_hi:[1,0]
	v_add_f32_e32 v53, 1.0, v53
	v_rcp_f32_e32 v56, v53
	v_add_f32_e32 v53, 1.0, v57
	v_rcp_f32_e32 v57, v53
	v_pk_mul_f32 v[48:49], v[54:55], v[48:49]
	v_lshl_add_u64 v[82:83], v[82:83], 0, s[44:45]
	v_cvt_pk_bf16_f32 v58, v48, v49
	v_pk_mul_f32 v[48:49], v[50:51], v[52:53] op_sel_hi:[1,0]
	v_lshlrev_b64 v[52:53], 7, v[72:73]
	v_pk_mul_f32 v[48:49], v[56:57], v[48:49]
	v_lshl_add_u64 v[56:57], v[76:77], 0, v[52:53]
	v_cvt_pk_bf16_f32 v59, v48, v49
	ds_read_b128 v[48:51], v198
	ds_read_b128 v[52:55], v198 offset:16
	global_store_dwordx2 v[56:57], v[58:59], off
	ds_read_b128 v[56:59], v207
	v_add_u32_e32 v72, -16, v92
	s_waitcnt lgkmcnt(2)
	v_add_f32_e32 v60, v48, v49
	v_add_f32_e32 v62, v50, v51
	s_waitcnt lgkmcnt(1)
	v_add_f32_e32 v52, v52, v53
	v_add_f32_e32 v54, v54, v55
	s_waitcnt lgkmcnt(0)
	v_mov_b32_e32 v61, v56
	v_mov_b32_e32 v63, v57
	v_mov_b32_e32 v53, v58
	v_mov_b32_e32 v55, v59
	v_pk_add_f32 v[56:57], v[60:61], v[62:63]
	v_pk_add_f32 v[52:53], v[52:53], v[54:55]
	v_and_b32_e32 v54, 0xffff0000, v112
	v_pk_add_f32 v[52:53], v[56:57], v[52:53]
	v_mul_f32_e32 v54, 0xbfb8aa3b, v54
	v_add_f32_e32 v52, v52, v53
	v_lshlrev_b32_e32 v53, 16, v112
	v_mul_f32_e32 v53, 0xbfb8aa3b, v53
	v_exp_f32_e32 v53, v53
	v_mul_f32_e32 v58, 0xbfb8aa3b, v68
	v_exp_f32_e32 v55, v54
	v_exp_f32_e32 v58, v58
	v_add_f32_e32 v53, 1.0, v53
	v_lshlrev_b32_e32 v56, 16, v113
	v_rcp_f32_e32 v54, v53
	v_add_f32_e32 v53, 1.0, v55
	v_max_f32_e64 v52, |v52|, v58
	v_and_b32_e32 v57, 0xffff0000, v113
	v_rcp_f32_e32 v55, v53
	v_mul_f32_e32 v53, 0xbfb8aa3b, v56
	v_rcp_f32_e32 v52, v52
	v_exp_f32_e32 v53, v53
	v_mul_f32_e32 v56, 0xbfb8aa3b, v57
	v_exp_f32_e32 v57, v56
	ds_read_b128 v[48:51], v199
	v_pk_mul_f32 v[44:45], v[44:45], v[52:53] op_sel_hi:[1,0]
	v_add_f32_e32 v53, 1.0, v53
	v_rcp_f32_e32 v56, v53
	v_add_f32_e32 v53, 1.0, v57
	v_rcp_f32_e32 v57, v53
	v_pk_mul_f32 v[44:45], v[54:55], v[44:45]
	v_lshl_add_u64 v[84:85], v[84:85], 0, s[44:45]
	v_cvt_pk_bf16_f32 v54, v44, v45
	v_pk_mul_f32 v[44:45], v[46:47], v[52:53] op_sel_hi:[1,0]
	v_lshl_add_u64 v[86:87], v[86:87], 0, s[46:47]
	v_pk_mul_f32 v[44:45], v[56:57], v[44:45]
	v_lshl_add_u64 v[88:89], v[88:89], 0, s[46:47]
	v_cvt_pk_bf16_f32 v55, v44, v45
	v_lshlrev_b64 v[44:45], 7, v[72:73]
	v_lshl_add_u64 v[52:53], v[76:77], 0, v[44:45]
	ds_read_b128 v[44:47], v199 offset:16
	global_store_dwordx2 v[52:53], v[54:55], off
	ds_read_b128 v[52:55], v208
	s_waitcnt lgkmcnt(2)
	v_add_f32_e32 v48, v48, v49
	v_add_f32_e32 v50, v50, v51
	s_waitcnt lgkmcnt(1)
	v_add_f32_e32 v44, v44, v45
	v_add_f32_e32 v46, v46, v47
	s_waitcnt lgkmcnt(0)
	v_mov_b32_e32 v49, v52
	v_mov_b32_e32 v51, v53
	v_mov_b32_e32 v45, v54
	v_mov_b32_e32 v47, v55
	v_pk_add_f32 v[48:49], v[48:49], v[50:51]
	v_pk_add_f32 v[44:45], v[44:45], v[46:47]
	v_and_b32_e32 v46, 0xffff0000, v110
	v_pk_add_f32 v[44:45], v[48:49], v[44:45]
	v_mul_f32_e32 v46, 0xbfb8aa3b, v46
	v_add_f32_e32 v44, v44, v45
	v_lshlrev_b32_e32 v45, 16, v110
	v_mul_f32_e32 v45, 0xbfb8aa3b, v45
	v_exp_f32_e32 v45, v45
	v_mul_f32_e32 v50, 0xbfb8aa3b, v69
	v_exp_f32_e32 v47, v46
	v_exp_f32_e32 v50, v50
	v_add_f32_e32 v45, 1.0, v45
	v_lshlrev_b32_e32 v48, 16, v111
	v_rcp_f32_e32 v46, v45
	v_add_f32_e32 v45, 1.0, v47
	v_max_f32_e64 v44, |v44|, v50
	v_and_b32_e32 v49, 0xffff0000, v111
	v_rcp_f32_e32 v47, v45
	v_mul_f32_e32 v45, 0xbfb8aa3b, v48
	v_rcp_f32_e32 v44, v44
	v_exp_f32_e32 v45, v45
	v_mul_f32_e32 v48, 0xbfb8aa3b, v49
	v_exp_f32_e32 v49, v48
	v_lshl_add_u64 v[90:91], v[90:91], 0, s[46:47]
	v_pk_mul_f32 v[40:41], v[40:41], v[44:45] op_sel_hi:[1,0]
	v_add_f32_e32 v45, 1.0, v45
	v_rcp_f32_e32 v48, v45
	v_add_f32_e32 v45, 1.0, v49
	v_rcp_f32_e32 v49, v45
	v_pk_mul_f32 v[42:43], v[42:43], v[44:45] op_sel_hi:[1,0]
	v_pk_mul_f32 v[40:41], v[46:47], v[40:41]
	v_lshl_add_u64 v[94:95], v[94:95], 0, s[46:47]
	v_pk_mul_f32 v[42:43], v[48:49], v[42:43]
	v_cvt_pk_bf16_f32 v40, v40, v41
	v_cvt_pk_bf16_f32 v41, v42, v43
	v_lshlrev_b64 v[42:43], 7, v[92:93]
	v_lshl_add_u64 v[42:43], v[76:77], 0, v[42:43]
	global_store_dwordx2 v[42:43], v[40:41], off
	s_waitcnt lgkmcnt(0)
	s_barrier
	v_add_u32_e32 v92, 0x80, v92
	s_andn2_b64 vcc, exec, s[66:67]
	s_cbranch_vccz .LBB0_2213

.LBB0_2187:
	ds_write_b128 v166, v[0:3]
	ds_write_b128 v166, v[4:7] offset:9216
	ds_write_b128 v166, v[8:11] offset:18432
	ds_read_b128 v[42:45], v167
	ds_read_b128 v[46:49], v167 offset:16
	v_max_f32_e32 v41, v160, v160
	v_lshlrev_b32_e32 v54, 16, v0
	v_and_b32_e32 v55, 0xffff0000, v1
	s_waitcnt lgkmcnt(1)
	v_mov_b32_e32 v52, v43
	v_mov_b32_e32 v43, v45
	v_max_f32_e32 v40, v40, v41
	v_and_b32_e32 v50, 0xffff0000, v0
	v_lshlrev_b32_e32 v51, 16, v1
	v_mov_b32_e32 v53, v44
	v_pk_mul_f32 v[42:43], v[42:43], v[54:55]
	v_sub_f32_e32 v40, v101, v40
	v_pk_fma_f32 v[42:43], v[52:53], v[50:51], v[42:43]
	s_waitcnt lgkmcnt(0)
	v_mov_b32_e32 v51, v48
	v_and_b32_e32 v53, 0xffff0000, v3
	v_and_b32_e32 v52, 0xffff0000, v2
	v_mov_b32_e32 v48, v47
	v_mul_f32_e32 v40, 0x3fb8aa3b, v40
	v_lshlrev_b32_e32 v45, 16, v3
	v_lshlrev_b32_e32 v44, 16, v2
	v_mov_b32_e32 v50, v46
	v_pk_mul_f32 v[46:47], v[48:49], v[52:53]
	v_exp_f32_e32 v40, v40
	v_pk_fma_f32 v[44:45], v[50:51], v[44:45], v[46:47]
	v_add_f32_e32 v41, v42, v43
	s_cmpk_lt_u32 s3, 0x7e
	v_add_f32_e32 v41, v44, v41
	s_cselect_b64 s[72:73], -1, 0
	s_cmpk_gt_u32 s3, 0x7d
	v_add_f32_e32 v41, v45, v41
	s_cselect_b64 s[66:67], -1, 0
	v_mul_f32_e32 v40, v40, v41
	s_and_b64 vcc, exec, s[66:67]
	v_lshl_add_u64 v[146:147], s[48:49], 0, v[86:87]
	v_lshl_add_u64 v[144:145], s[48:49], 0, v[88:89]
	v_lshl_add_u64 v[142:143], s[48:49], 0, v[90:91]
	v_lshl_add_u64 v[140:141], s[48:49], 0, v[94:95]
	v_lshl_add_u64 v[138:139], s[48:49], 0, v[84:85]
	v_lshl_add_u64 v[136:137], s[48:49], 0, v[82:83]
	v_lshl_add_u64 v[134:135], s[48:49], 0, v[78:79]
	ds_write_b32 v168, v40
	ds_write_b128 v169, v[28:31] offset:27648
	ds_write_b128 v170, v[20:23] offset:27648
	s_cbranch_vccnz .LBB0_2189
	v_add_co_u32_e32 v0, vcc, 0x51b8c000, v146
	s_nop 1
	v_addc_co_u32_e32 v1, vcc, 0, v147, vcc
	v_add_co_u32_e32 v4, vcc, 0x51b8e000, v146
	s_nop 1
	v_addc_co_u32_e32 v5, vcc, 0, v147, vcc
	v_add_co_u32_e32 v8, vcc, 0x51b90000, v146
	global_load_dwordx4 v[0:3], v[0:1], off offset:2048
	s_nop 0
	global_load_dwordx4 v[4:7], v[4:5], off offset:2048
	v_addc_co_u32_e32 v9, vcc, 0, v147, vcc
	v_add_co_u32_e32 v20, vcc, 0x51b92000, v144
	s_nop 1
	v_addc_co_u32_e32 v21, vcc, 0, v145, vcc
	global_load_dwordx4 v[8:11], v[8:9], off offset:2048
	s_nop 0
	global_load_dword v149, v[20:21], off offset:2048
	global_load_dword v151, v[20:21], off offset:2304
	global_load_dword v156, v[20:21], off offset:2560
	v_add_co_u32_e32 v20, vcc, 0x51b92000, v142
	s_nop 1
	v_addc_co_u32_e32 v21, vcc, 0, v143, vcc
	v_add_co_u32_e32 v22, vcc, 0x51b92000, v140
	s_nop 1
	v_addc_co_u32_e32 v23, vcc, 0, v141, vcc
	v_add_co_u32_e32 v28, vcc, 0x40810000, v138
	s_nop 1
	v_addc_co_u32_e32 v29, vcc, 0, v139, vcc
	global_load_dword v160, v[20:21], off offset:2304
	global_load_dword v203, v[22:23], off offset:2816
	s_nop 0
	global_load_dwordx4 v[28:31], v[28:29], off
	v_add_co_u32_e32 v20, vcc, 0x40810000, v136
	s_nop 1
	v_addc_co_u32_e32 v21, vcc, 0, v137, vcc
	v_add_co_u32_e32 v40, vcc, 0x2a810000, v134
	s_nop 1
	v_addc_co_u32_e32 v41, vcc, 0, v135, vcc
	global_load_dwordx4 v[20:23], v[20:21], off
	s_nop 0
	global_load_dwordx2 v[102:103], v[40:41], off
	v_add_co_u32_e32 v40, vcc, 0x2a812000, v134
	s_nop 1
	v_addc_co_u32_e32 v41, vcc, 0, v135, vcc
	v_add_co_u32_e32 v42, vcc, 0x2a814000, v134
	s_nop 1
	v_addc_co_u32_e32 v43, vcc, 0, v135, vcc
	v_add_co_u32_e32 v44, vcc, 0x2a816000, v134
	s_nop 1
	v_addc_co_u32_e32 v45, vcc, 0, v135, vcc
	global_load_dwordx2 v[104:105], v[40:41], off
	global_load_dwordx2 v[106:107], v[42:43], off
	global_load_dwordx2 v[108:109], v[44:45], off

.LBB0_2201:
	ds_write_b128 v166, v[12:15]
	ds_write_b128 v166, v[16:19] offset:9216
	ds_write_b128 v166, v[24:27] offset:18432
	ds_read_b128 v[40:43], v167
	ds_read_b128 v[44:47], v167 offset:16
	v_lshlrev_b32_e32 v52, 16, v12
	v_and_b32_e32 v53, 0xffff0000, v13
	v_and_b32_e32 v48, 0xffff0000, v12
	s_waitcnt lgkmcnt(1)
	v_mov_b32_e32 v50, v41
	v_mov_b32_e32 v41, v43
	v_lshlrev_b32_e32 v49, 16, v13
	v_mov_b32_e32 v51, v42
	v_pk_mul_f32 v[40:41], v[40:41], v[52:53]
	v_lshlrev_b32_e32 v43, 16, v15
	v_pk_fma_f32 v[40:41], v[50:51], v[48:49], v[40:41]
	s_waitcnt lgkmcnt(0)
	v_mov_b32_e32 v49, v46
	v_and_b32_e32 v51, 0xffff0000, v15
	v_and_b32_e32 v50, 0xffff0000, v14
	v_mov_b32_e32 v46, v45
	v_lshlrev_b32_e32 v42, 16, v14
	v_mov_b32_e32 v48, v44
	v_pk_mul_f32 v[44:45], v[46:47], v[50:51]
	v_add_f32_e32 v40, v40, v41
	v_pk_fma_f32 v[42:43], v[48:49], v[42:43], v[44:45]
	v_max_f32_e32 v44, v165, v165
	v_max_f32_e32 v45, v209, v209
	v_max_f32_e32 v44, v45, v44
	v_sub_f32_e32 v44, v209, v44
	v_mul_f32_e32 v44, 0x3fb8aa3b, v44
	v_exp_f32_e32 v44, v44
	v_add_f32_e32 v40, v42, v40
	v_add_f32_e32 v40, v43, v40
	s_andn2_b64 vcc, exec, s[72:73]
	v_mul_f32_e32 v40, v44, v40
	ds_write_b32 v168, v40
	ds_write_b128 v169, v[32:35] offset:27648
	ds_write_b128 v170, v[36:39] offset:27648
	s_cbranch_vccnz .LBB0_2203
	v_add_co_u32_e32 v12, vcc, 0x51b92000, v146
	s_nop 1
	v_addc_co_u32_e32 v13, vcc, 0, v147, vcc
	v_add_co_u32_e32 v16, vcc, 0x51b94000, v146
	s_nop 1
	v_addc_co_u32_e32 v17, vcc, 0, v147, vcc
	v_add_co_u32_e32 v24, vcc, 0x51b96000, v146
	global_load_dwordx4 v[12:15], v[12:13], off offset:3072
	s_nop 0
	global_load_dwordx4 v[16:19], v[16:17], off offset:3072
	v_addc_co_u32_e32 v25, vcc, 0, v147, vcc
	v_add_co_u32_e32 v32, vcc, 0x51b98000, v144
	s_nop 1
	v_addc_co_u32_e32 v33, vcc, 0, v145, vcc
	global_load_dwordx4 v[24:27], v[24:25], off offset:3072
	s_nop 0
	global_load_dword v157, v[32:33], off offset:3072
	global_load_dword v158, v[32:33], off offset:3328
	global_load_dword v159, v[32:33], off offset:3584
	v_add_co_u32_e32 v32, vcc, 0x51b98000, v142
	s_nop 1
	v_addc_co_u32_e32 v33, vcc, 0, v143, vcc
	v_add_co_u32_e32 v34, vcc, 0x51b98000, v140
	s_nop 1
	v_addc_co_u32_e32 v35, vcc, 0, v141, vcc
	v_add_co_u32_e32 v36, vcc, 0x40818000, v138
	s_nop 1
	v_addc_co_u32_e32 v37, vcc, 0, v139, vcc
	global_load_dword v165, v[32:33], off offset:3328
	global_load_dword v100, v[34:35], off offset:3840
	s_nop 0
	global_load_dwordx4 v[32:35], v[36:37], off
	v_add_co_u32_e32 v36, vcc, 0x40818000, v136
	s_nop 1
	v_addc_co_u32_e32 v37, vcc, 0, v137, vcc
	v_add_co_u32_e32 v40, vcc, 0x2a818000, v134
	s_nop 1
	v_addc_co_u32_e32 v41, vcc, 0, v135, vcc
	global_load_dwordx4 v[36:39], v[36:37], off
	s_nop 0
	global_load_dwordx2 v[98:99], v[40:41], off
	v_add_co_u32_e32 v40, vcc, 0x2a81a000, v134
	s_nop 1
	v_addc_co_u32_e32 v41, vcc, 0, v135, vcc
	v_add_co_u32_e32 v42, vcc, 0x2a81c000, v134
	s_nop 1
	v_addc_co_u32_e32 v43, vcc, 0, v135, vcc
	v_add_co_u32_e32 v44, vcc, 0x2a81e000, v134
	s_nop 1
	v_addc_co_u32_e32 v45, vcc, 0, v135, vcc
	global_load_dwordx2 v[96:97], v[40:41], off
	global_load_dwordx2 v[80:81], v[42:43], off
	global_load_dwordx2 v[74:75], v[44:45], off
